# hazard-pad cleanup (asm guide 4.1 a/b): removable XNACK s_nop 0 between VMEM ops, the post-asm s_nop 0 and a dead vmcnt(4) deleted from the attention loop, on top of v32
# speedup vs baseline: 1.0082x; 1.0049x over previous
; #define SLOAD(i, k0) do { sr_[i].vs0 = ld8(&Vh[(long)((k0) + sr) * LDK + sc]); sr_[i].vs1 = ld8(&Vh[(long)((k0) + 32 + sr) * LDK + sc]); \
;     sr_[i].ks0 = ld8(&Kh[(long)((k0) + sr) * LDK + sc]); sr_[i].ks1 = ld8(&Kh[(long)((k0) + 32 + sr) * LDK + sc]); } while (0)
; #define SWAIT() asm volatile("s_waitcnt vmcnt(4)" ::: "memory")
; #define SWRITE_I(B, i) do { LDSV(wv0 + (B) * 16384) = sr_[i].vs0; LDSV(wv1 + (B) * 16384) = sr_[i].vs1; LDSV(wk0 + (B) * 16384) = sr_[i].ks0; LDSV(wk1 + (B) * 16384) = sr_[i].ks1; } while (0)
; __device__ __forceinline__ void finishSM(f32x16& p0, f32x16& p1, float alpha, float& l_reg, bf16x8& pa0, bf16x8& pa1, bf16x8& pa2, bf16x8& pa3) {
;   for (int r = 0; r < 16; ++r) p1[r] = __builtin_amdgcn_exp2f(p1[r]);
;   float ps = 0; for (int r = 0; r < 16; ++r) ps += p0[r]; for (int r = 0; r < 16; ++r) ps += p1[r];
;   { auto rr = __builtin_amdgcn_permlane32_swap(__float_as_uint(ps), __float_as_uint(ps), false, false);
;     ps = __uint_as_float(rr[0]) + __uint_as_float(rr[1]); }
;   l_reg = l_reg * alpha + ps;
;     ...
;   PK4(p0, 0, pa0); PK4(p0, 8, pa1); PK4(p1, 0, pa2); PK4(p1, 8, pa3);
;     ...
; }
; template <bool PARTIAL, bool FIXED> ...
;     ...
;   int j = 1;
;   for (; j + 6 < NT; j += 6) {
;     HALF_B(1, 0, SLOAD(1, (j + 2) * KVBLK), do { SWAIT(); SWRITE_I(2, 0); } while (0));
.LBB0_352:
	s_waitcnt lgkmcnt(0)
	s_barrier
	ds_read_b128 v[80:83], v207 offset:16384
	ds_read_b128 v[84:87], v207 offset:24576
	ds_read_b128 v[162:165], v208 offset:16384
	ds_read_b128 v[166:169], v208 offset:24576
	v_exp_f32_e32 v170, v72
	v_exp_f32_e32 v171, v73
	v_exp_f32_e32 v172, v74
	v_exp_f32_e32 v173, v75
	v_exp_f32_e32 v174, v76
	v_exp_f32_e32 v175, v77
	v_exp_f32_e32 v176, v78
	v_exp_f32_e32 v79, v79
	s_waitcnt lgkmcnt(3)
	v_mfma_f32_32x32x16_bf16 v[96:111], v[80:83], v[142:145], 0
	v_exp_f32_e32 v236, v64
	v_add_f32_e32 v64, 0, v229
	v_add_f32_e32 v64, v243, v64
	v_add_f32_e32 v64, v244, v64
	s_waitcnt lgkmcnt(2)
	v_mfma_f32_32x32x16_bf16 v[80:95], v[84:87], v[142:145], 0
	v_add_f32_e32 v64, v246, v64
	v_add_f32_e32 v64, v242, v64
	v_add_f32_e32 v64, v245, v64
	s_waitcnt lgkmcnt(1)
	v_mfma_f32_32x32x16_bf16 v[96:111], v[162:165], v[138:141], v[96:111]
	v_add_f32_e32 v64, v227, v64
	v_add_f32_e32 v64, v228, v64
	v_add_f32_e32 v64, v223, v64
	s_waitcnt lgkmcnt(0)
	v_mfma_f32_32x32x16_bf16 v[80:95], v[166:169], v[138:141], v[80:95]
	ds_read_b128 v[162:165], v209 offset:16384
	ds_read_b128 v[166:169], v209 offset:24576
	v_add_f32_e32 v64, v226, v64
	v_add_f32_e32 v64, v224, v64
	v_add_f32_e32 v64, v225, v64
	v_add_f32_e32 v64, v220, v64
	v_exp_f32_e32 v237, v65
	s_waitcnt lgkmcnt(1)
	v_mfma_f32_32x32x16_bf16 v[96:111], v[162:165], v[112:115], v[96:111]
	v_add_f32_e32 v64, v222, v64
	v_exp_f32_e32 v238, v66
	v_add_f32_e32 v64, v219, v64
	v_exp_f32_e32 v239, v67
	s_waitcnt lgkmcnt(0)
	v_mfma_f32_32x32x16_bf16 v[80:95], v[166:169], v[112:115], v[80:95]
	ds_read_b128 v[162:165], v210 offset:16384
	ds_read_b128 v[166:169], v210 offset:24576
	v_add_f32_e32 v64, v221, v64
	v_exp_f32_e32 v247, v68
	v_add_f32_e32 v64, v236, v64
	v_exp_f32_e32 v248, v69
	s_waitcnt lgkmcnt(1)
	v_mfma_f32_32x32x16_bf16 v[96:111], v[162:165], v[116:119], v[96:111]
	v_add_f32_e32 v64, v237, v64
	v_exp_f32_e32 v249, v70
	v_add_f32_e32 v64, v238, v64
	v_exp_f32_e32 v252, v71
	s_waitcnt lgkmcnt(0)
	v_mfma_f32_32x32x16_bf16 v[80:95], v[166:169], v[116:119], v[80:95]
	ds_read_b128 v[162:165], v190 offset:16384
	ds_read_b128 v[166:169], v190 offset:24576
	v_add_f32_e32 v64, v239, v64
	v_add_f32_e32 v64, v247, v64
	v_add_f32_e32 v64, v248, v64
	v_add_f32_e32 v64, v249, v64
	v_add_f32_e32 v64, v252, v64
	v_add_f32_e32 v64, v170, v64
	s_waitcnt lgkmcnt(1)
	v_mfma_f32_32x32x16_bf16 v[96:111], v[162:165], v[120:123], v[96:111]
	v_add_f32_e32 v64, v171, v64
	v_add_f32_e32 v64, v172, v64
	v_add_f32_e32 v64, v173, v64
	v_add_f32_e32 v64, v174, v64
	v_add_f32_e32 v64, v175, v64
	s_waitcnt lgkmcnt(0)
	v_mfma_f32_32x32x16_bf16 v[80:95], v[166:169], v[120:123], v[80:95]
	ds_read_b128 v[162:165], v191 offset:16384
	ds_read_b128 v[166:169], v191 offset:24576
	v_add_f32_e32 v64, v176, v64
	v_add_f32_e32 v64, v79, v64
	v_mov_b32_e32 v65, v64
	s_nop 1
	v_permlane32_swap_b32_e32 v64, v65
	v_add_f32_e32 v64, v64, v65
	s_waitcnt lgkmcnt(1)
	v_mfma_f32_32x32x16_bf16 v[96:111], v[162:165], v[124:127], v[96:111]
	v_add_f32_e32 v128, v215, v64
	v_cvt_pk_bf16_f32 v64, v229, v243
	v_cvt_pk_bf16_f32 v65, v244, v246
	v_cvt_pk_bf16_f32 v66, v242, v245
	v_cvt_pk_bf16_f32 v67, v227, v228
	s_waitcnt lgkmcnt(0)
	v_mfma_f32_32x32x16_bf16 v[80:95], v[166:169], v[124:127], v[80:95]
	ds_read_b128 v[162:165], v192 offset:16384
	ds_read_b128 v[166:169], v192 offset:24576
	v_cvt_pk_bf16_f32 v68, v223, v226
	v_cvt_pk_bf16_f32 v69, v224, v225
	v_cvt_pk_bf16_f32 v70, v220, v222
	v_cvt_pk_bf16_f32 v71, v219, v221
	v_cvt_pk_bf16_f32 v72, v236, v237
	v_cvt_pk_bf16_f32 v73, v238, v239
	s_waitcnt lgkmcnt(1)
	v_mfma_f32_32x32x16_bf16 v[96:111], v[162:165], v[130:133], v[96:111]
	v_cvt_pk_bf16_f32 v74, v247, v248
	v_cvt_pk_bf16_f32 v75, v249, v252
	v_cvt_pk_bf16_f32 v76, v170, v171
	v_cvt_pk_bf16_f32 v77, v172, v173
	v_cvt_pk_bf16_f32 v78, v174, v175
	s_waitcnt lgkmcnt(0)
	v_mfma_f32_32x32x16_bf16 v[80:95], v[166:169], v[130:133], v[80:95]
	ds_read_b128 v[162:165], v193 offset:16384
	ds_read_b128 v[166:169], v193 offset:24576
	ds_read_b64_tr_b16 v[180:181], v206 offset:0
	ds_read_b64_tr_b16 v[182:183], v206 offset:0x800
	ds_read_b64_tr_b16 v[184:185], v206 offset:0x1000
	ds_read_b64_tr_b16 v[186:187], v206 offset:0x1800
	ds_read_b64_tr_b16 v[216:217], v206 offset:0x2000
	ds_read_b64_tr_b16 v[218:219], v206 offset:0x2800
	ds_read_b64_tr_b16 v[220:221], v206 offset:0x3000
	ds_read_b64_tr_b16 v[222:223], v206 offset:0x3800
	v_cvt_pk_bf16_f32 v79, v176, v79
	s_nop 0
	v_permlane32_swap_b32_e32 v64, v66
	v_permlane32_swap_b32_e32 v65, v67
	v_permlane32_swap_b32_e32 v68, v70
	v_permlane32_swap_b32_e32 v69, v71
	s_waitcnt lgkmcnt(9)
	v_mfma_f32_32x32x16_bf16 v[96:111], v[162:165], v[134:137], v[96:111]
	v_permlane32_swap_b32_e32 v72, v74
	v_permlane32_swap_b32_e32 v73, v75
	v_permlane32_swap_b32_e32 v76, v78
	v_permlane32_swap_b32_e32 v77, v79
	s_waitcnt lgkmcnt(8)
	v_mfma_f32_32x32x16_bf16 v[80:95], v[166:169], v[134:137], v[80:95]
	s_waitcnt vmcnt(0)
	ds_write_b128 v211, v[146:149] offset:32768
	s_waitcnt lgkmcnt(7)
	v_mfma_f32_32x32x16_bf16 v[0:15], v[64:67], v[180:183], v[0:15]
	ds_read_b64_tr_b16 v[180:181], v206 offset:0x200
	ds_read_b64_tr_b16 v[182:183], v206 offset:0xa00
	v_add_co_u32_e32 v166, vcc, s19, v178
	s_nop 1
	v_addc_co_u32_e32 v167, vcc, -1, v179, vcc
	v_add_co_u32_e32 v170, vcc, s20, v178
	s_nop 1
	v_addc_co_u32_e32 v171, vcc, -1, v179, vcc
	s_waitcnt lgkmcnt(7)
	v_mfma_f32_32x32x16_bf16 v[0:15], v[68:71], v[184:187], v[0:15]
	ds_read_b64_tr_b16 v[184:185], v206 offset:0x1200
	ds_read_b64_tr_b16 v[186:187], v206 offset:0x1a00
	global_load_dwordx4 v[162:165], v[166:167], off
	global_load_dwordx4 v[166:169], v[166:167], off offset:-512
	global_load_dwordx4 v[174:177], v[170:171], off
	global_load_dwordx4 v[170:173], v[170:171], off offset:-512
	s_waitcnt lgkmcnt(7)
; #define SLOAD(i, k0) do { sr_[i].vs0 = ld8(&Vh[(long)((k0) + sr) * LDK + sc]); sr_[i].vs1 = ld8(&Vh[(long)((k0) + 32 + sr) * LDK + sc]); \
;     sr_[i].ks0 = ld8(&Kh[(long)((k0) + sr) * LDK + sc]); sr_[i].ks1 = ld8(&Kh[(long)((k0) + 32 + sr) * LDK + sc]); } while (0)
; #define SWAIT() asm volatile("s_waitcnt vmcnt(4)" ::: "memory")
; #define SWRITE_I(B, i) do { LDSV(wv0 + (B) * 16384) = sr_[i].vs0; LDSV(wv1 + (B) * 16384) = sr_[i].vs1; LDSV(wk0 + (B) * 16384) = sr_[i].ks0; LDSV(wk1 + (B) * 16384) = sr_[i].ks1; } while (0)
; #define NOP_() do { } while (0)
; template <int BOFF> __device__ __forceinline__ void qkt_i(f32x16& p0, f32x16& p1, const int (&kb)[4], const bf16x8* qr) {
;   p0 = f32x16{}; p1 = f32x16{};
; #pragma unroll
;   for (int d0 = 0; d0 < 8; ++d0) { const int off = BOFF + (d0 >> 2) * 128;
;     const bf16x8 b0 = LDSV(kb[d0 & 3] + off), b1 = LDSV(kb[d0 & 3] + off + 8192);
;     p0 = __builtin_amdgcn_mfma_f32_32x32x16_bf16(b0, qr[d0], p0, 0, 0, 0);
;     p1 = __builtin_amdgcn_mfma_f32_32x32x16_bf16(b1, qr[d0], p1, 0, 0, 0); }
; }
; template <bool PARTIAL, bool FIXED> ...
;     ...
;   int j = 1;
;   for (; j + 6 < NT; j += 6) {
;     HALF_B(1, 0, SLOAD(1, (j + 2) * KVBLK), do { SWAIT(); SWRITE_I(2, 0); } while (0));
;     HALF_A(2, 1, NOP_(), SLOAD(0, (j + 3) * KVBLK), do { SWAIT(); SWRITE_I(0, 1); } while (0));
	v_mfma_f32_32x32x16_bf16 v[0:15], v[72:75], v[216:219], v[0:15]
	ds_read_b64_tr_b16 v[216:217], v206 offset:0x2200
	ds_read_b64_tr_b16 v[218:219], v206 offset:0x2a00
	s_waitcnt lgkmcnt(7)
	v_mfma_f32_32x32x16_bf16 v[0:15], v[76:79], v[220:223], v[0:15]
	ds_read_b64_tr_b16 v[220:221], v206 offset:0x3200
	ds_read_b64_tr_b16 v[222:223], v206 offset:0x3a00
	ds_write_b128 v212, v[150:153] offset:32768
	s_waitcnt lgkmcnt(7)
	v_mfma_f32_32x32x16_bf16 v[16:31], v[64:67], v[180:183], v[16:31]
	ds_read_b64_tr_b16 v[180:181], v206 offset:0x400
	ds_read_b64_tr_b16 v[182:183], v206 offset:0xc00
	s_waitcnt lgkmcnt(7)
	v_mfma_f32_32x32x16_bf16 v[16:31], v[68:71], v[184:187], v[16:31]
	ds_read_b64_tr_b16 v[184:185], v206 offset:0x1400
	ds_read_b64_tr_b16 v[186:187], v206 offset:0x1c00
	s_waitcnt lgkmcnt(7)
	v_mfma_f32_32x32x16_bf16 v[16:31], v[72:75], v[216:219], v[16:31]
	ds_read_b64_tr_b16 v[216:217], v206 offset:0x2400
	ds_read_b64_tr_b16 v[218:219], v206 offset:0x2c00
	s_waitcnt lgkmcnt(7)
	v_mfma_f32_32x32x16_bf16 v[16:31], v[76:79], v[220:223], v[16:31]
	ds_read_b64_tr_b16 v[220:221], v206 offset:0x3400
	ds_read_b64_tr_b16 v[222:223], v206 offset:0x3c00
	ds_write_b128 v213, v[154:157] offset:32768
	s_waitcnt lgkmcnt(7)
	v_mfma_f32_32x32x16_bf16 v[32:47], v[64:67], v[180:183], v[32:47]
	ds_read_b64_tr_b16 v[180:181], v206 offset:0x600
	ds_read_b64_tr_b16 v[182:183], v206 offset:0xe00
	v_exp_f32_e32 v215, v108
	v_exp_f32_e32 v188, v102
	s_waitcnt lgkmcnt(7)
	v_mfma_f32_32x32x16_bf16 v[32:47], v[68:71], v[184:187], v[32:47]
	ds_read_b64_tr_b16 v[184:185], v206 offset:0x1600
	ds_read_b64_tr_b16 v[186:187], v206 offset:0x1e00
	v_exp_f32_e32 v189, v103
	v_exp_f32_e32 v196, v104
	s_waitcnt lgkmcnt(7)
	v_mfma_f32_32x32x16_bf16 v[32:47], v[72:75], v[216:219], v[32:47]
	ds_read_b64_tr_b16 v[216:217], v206 offset:0x2600
	ds_read_b64_tr_b16 v[218:219], v206 offset:0x2e00
	v_exp_f32_e32 v197, v105
	v_exp_f32_e32 v198, v106
	s_waitcnt lgkmcnt(7)
	v_mfma_f32_32x32x16_bf16 v[32:47], v[76:79], v[220:223], v[32:47]
	ds_read_b64_tr_b16 v[220:221], v206 offset:0x3600
	ds_read_b64_tr_b16 v[222:223], v206 offset:0x3e00
	v_exp_f32_e32 v199, v107
	ds_write_b128 v214, v[158:161] offset:32768
	s_waitcnt lgkmcnt(7)
	v_mfma_f32_32x32x16_bf16 v[48:63], v[64:67], v[180:183], v[48:63]
	v_exp_f32_e32 v181, v96
	v_exp_f32_e32 v183, v97
	s_waitcnt lgkmcnt(5)
	v_mfma_f32_32x32x16_bf16 v[48:63], v[68:71], v[184:187], v[48:63]
	v_exp_f32_e32 v184, v98
	v_exp_f32_e32 v185, v99
	v_exp_f32_e32 v186, v100
	v_exp_f32_e32 v187, v101
	s_waitcnt lgkmcnt(3)
	v_mfma_f32_32x32x16_bf16 v[48:63], v[72:75], v[216:219], v[48:63]
	v_exp_f32_e32 v216, v109
	v_exp_f32_e32 v217, v110
	v_exp_f32_e32 v218, v111
	s_waitcnt lgkmcnt(0)
	s_barrier
	v_mfma_f32_32x32x16_bf16 v[48:63], v[76:79], v[220:223], v[48:63]
	ds_read_b128 v[64:67], v207 offset:32768
	ds_read_b128 v[96:99], v207 offset:40960
	ds_read_b128 v[146:149], v208 offset:32768
	ds_read_b128 v[150:153], v208 offset:40960
	v_exp_f32_e32 v154, v88
	v_exp_f32_e32 v155, v89
	v_exp_f32_e32 v156, v90
	v_exp_f32_e32 v157, v91
	v_exp_f32_e32 v158, v92
	v_exp_f32_e32 v159, v93
	v_exp_f32_e32 v160, v94
	v_exp_f32_e32 v95, v95
	s_waitcnt lgkmcnt(3)
	v_mfma_f32_32x32x16_bf16 v[64:79], v[64:67], v[142:145], 0
	v_exp_f32_e32 v236, v80
	v_add_f32_e32 v80, 0, v181
	v_add_f32_e32 v80, v183, v80
	v_add_f32_e32 v80, v184, v80
	s_waitcnt lgkmcnt(2)
	v_mfma_f32_32x32x16_bf16 v[96:111], v[96:99], v[142:145], 0
	v_add_f32_e32 v80, v185, v80
	v_add_f32_e32 v80, v186, v80
	v_add_f32_e32 v80, v187, v80
	s_waitcnt lgkmcnt(1)
	v_mfma_f32_32x32x16_bf16 v[64:79], v[146:149], v[138:141], v[64:79]
	v_add_f32_e32 v80, v188, v80
	v_add_f32_e32 v80, v189, v80
	v_add_f32_e32 v80, v196, v80
	s_waitcnt lgkmcnt(0)
	v_mfma_f32_32x32x16_bf16 v[96:111], v[150:153], v[138:141], v[96:111]
	ds_read_b128 v[146:149], v209 offset:32768
	ds_read_b128 v[150:153], v209 offset:40960
	v_add_f32_e32 v80, v197, v80
	v_add_f32_e32 v80, v198, v80
	v_add_f32_e32 v80, v199, v80
	v_add_f32_e32 v80, v215, v80
	v_exp_f32_e32 v237, v81
	s_waitcnt lgkmcnt(1)
	v_mfma_f32_32x32x16_bf16 v[64:79], v[146:149], v[112:115], v[64:79]
	v_add_f32_e32 v80, v216, v80
	v_exp_f32_e32 v238, v82
	v_add_f32_e32 v80, v217, v80
	v_exp_f32_e32 v239, v83
	s_waitcnt lgkmcnt(0)
	v_mfma_f32_32x32x16_bf16 v[96:111], v[150:153], v[112:115], v[96:111]
	ds_read_b128 v[146:149], v210 offset:32768
	ds_read_b128 v[150:153], v210 offset:40960
	v_add_f32_e32 v80, v218, v80
	v_exp_f32_e32 v247, v84
	v_add_f32_e32 v80, v236, v80
	v_exp_f32_e32 v248, v85
	s_waitcnt lgkmcnt(1)
	v_mfma_f32_32x32x16_bf16 v[64:79], v[146:149], v[116:119], v[64:79]
	v_add_f32_e32 v80, v237, v80
	v_exp_f32_e32 v249, v86
	v_add_f32_e32 v80, v238, v80
	v_exp_f32_e32 v252, v87
	s_waitcnt lgkmcnt(0)
	v_mfma_f32_32x32x16_bf16 v[96:111], v[150:153], v[116:119], v[96:111]
	ds_read_b128 v[146:149], v190 offset:32768
	ds_read_b128 v[150:153], v190 offset:40960
	v_add_f32_e32 v80, v239, v80
	v_add_f32_e32 v80, v247, v80
	v_add_f32_e32 v80, v248, v80
	v_add_f32_e32 v80, v249, v80
	v_add_f32_e32 v80, v252, v80
	v_add_f32_e32 v80, v154, v80
	s_waitcnt lgkmcnt(1)
	v_mfma_f32_32x32x16_bf16 v[64:79], v[146:149], v[120:123], v[64:79]
	v_add_f32_e32 v80, v155, v80
	v_add_f32_e32 v80, v156, v80
	v_add_f32_e32 v80, v157, v80
	v_add_f32_e32 v80, v158, v80
	v_add_f32_e32 v80, v159, v80
	s_waitcnt lgkmcnt(0)
	v_mfma_f32_32x32x16_bf16 v[96:111], v[150:153], v[120:123], v[96:111]
	ds_read_b128 v[146:149], v191 offset:32768
	ds_read_b128 v[150:153], v191 offset:40960
	v_add_f32_e32 v80, v160, v80
	v_add_f32_e32 v180, v95, v80
	v_mov_b32_e32 v182, v180
	v_cvt_pk_bf16_f32 v80, v181, v183
	v_cvt_pk_bf16_f32 v81, v184, v185
	v_cvt_pk_bf16_f32 v82, v186, v187
	s_waitcnt lgkmcnt(1)
; #define SBAR() __builtin_amdgcn_sched_barrier(0)
; #define SLOAD(i, k0) do { sr_[i].vs0 = ld8(&Vh[(long)((k0) + sr) * LDK + sc]); sr_[i].vs1 = ld8(&Vh[(long)((k0) + 32 + sr) * LDK + sc]); \
;     sr_[i].ks0 = ld8(&Kh[(long)((k0) + sr) * LDK + sc]); sr_[i].ks1 = ld8(&Kh[(long)((k0) + 32 + sr) * LDK + sc]); } while (0)
; #define SWAIT() asm volatile("s_waitcnt vmcnt(4)" ::: "memory")
; #define SWRITE_I(B, i) do { LDSV(wv0 + (B) * 16384) = sr_[i].vs0; LDSV(wv1 + (B) * 16384) = sr_[i].vs1; LDSV(wk0 + (B) * 16384) = sr_[i].ks0; LDSV(wk1 + (B) * 16384) = sr_[i].ks1; } while (0)
; #define NOP_() do { } while (0)
; template <int D0, int BOFF> __device__ __forceinline__ void pv_one_i(f32x16& od, int vb, bf16x8 pa0, bf16x8 pa1, bf16x8 pa2, bf16x8 pa3) {
;   const s16x4 l0 = tr_read<BOFF + v_rd_off(D0, 0, 0)>(vb), h0 = tr_read<BOFF + v_rd_off(D0, 0, 1)>(vb), l1 = tr_read<BOFF + v_rd_off(D0, 1, 0)>(vb), h1 = tr_read<BOFF + v_rd_off(D0, 1, 1)>(vb);
;   const s16x4 l2 = tr_read<BOFF + v_rd_off(D0, 2, 0)>(vb), h2 = tr_read<BOFF + v_rd_off(D0, 2, 1)>(vb), l3 = tr_read<BOFF + v_rd_off(D0, 3, 0)>(vb), h3 = tr_read<BOFF + v_rd_off(D0, 3, 1)>(vb);
;   asm volatile("s_waitcnt lgkmcnt(0)" ::: "memory"); SBAR();
;     ...
;   od = __builtin_amdgcn_mfma_f32_32x32x16_bf16(pa0, PK(l0, h0), od, 0, 0, 0);
;   od = __builtin_amdgcn_mfma_f32_32x32x16_bf16(pa1, PK(l1, h1), od, 0, 0, 0);
;   od = __builtin_amdgcn_mfma_f32_32x32x16_bf16(pa2, PK(l2, h2), od, 0, 0, 0);
;   od = __builtin_amdgcn_mfma_f32_32x32x16_bf16(pa3, PK(l3, h3), od, 0, 0, 0);
;     ...
; }
; template <int BOFF> __device__ __forceinline__ void pv_i(f32x16* o, int vb, bf16x8 pa0, bf16x8 pa1, bf16x8 pa2, bf16x8 pa3) {
;   pv_one_i<0, BOFF>(o[0], vb, pa0, pa1, pa2, pa3); pv_one_i<1, BOFF>(o[1], vb, pa0, pa1, pa2, pa3); pv_one_i<2, BOFF>(o[2], vb, pa0, pa1, pa2, pa3); pv_one_i<3, BOFF>(o[3], vb, pa0, pa1, pa2, pa3);
; template <bool PARTIAL, bool FIXED> ...
;     ...
;   int j = 1;
;   for (; j + 6 < NT; j += 6) {
;     HALF_B(1, 0, SLOAD(1, (j + 2) * KVBLK), do { SWAIT(); SWRITE_I(2, 0); } while (0));
;     HALF_A(2, 1, NOP_(), SLOAD(0, (j + 3) * KVBLK), do { SWAIT(); SWRITE_I(0, 1); } while (0));
	v_mfma_f32_32x32x16_bf16 v[64:79], v[146:149], v[124:127], v[64:79]
	v_cvt_pk_bf16_f32 v83, v188, v189
	v_cvt_pk_bf16_f32 v84, v196, v197
	v_cvt_pk_bf16_f32 v85, v198, v199
	v_cvt_pk_bf16_f32 v86, v215, v216
	v_cvt_pk_bf16_f32 v87, v217, v218
	s_waitcnt lgkmcnt(0)
	v_mfma_f32_32x32x16_bf16 v[96:111], v[150:153], v[124:127], v[96:111]
	ds_read_b128 v[146:149], v192 offset:32768
	ds_read_b128 v[150:153], v192 offset:40960
	v_cvt_pk_bf16_f32 v88, v236, v237
	v_cvt_pk_bf16_f32 v89, v238, v239
	v_cvt_pk_bf16_f32 v90, v247, v248
	v_cvt_pk_bf16_f32 v91, v249, v252
	v_cvt_pk_bf16_f32 v92, v154, v155
	v_cvt_pk_bf16_f32 v93, v156, v157
	s_waitcnt lgkmcnt(1)
	v_mfma_f32_32x32x16_bf16 v[64:79], v[146:149], v[130:133], v[64:79]
	v_cvt_pk_bf16_f32 v94, v158, v159
	v_cvt_pk_bf16_f32 v95, v160, v95
	s_nop 1
	v_permlane32_swap_b32_e32 v180, v182
	v_permlane32_swap_b32_e32 v80, v82
	s_waitcnt lgkmcnt(0)
	v_mfma_f32_32x32x16_bf16 v[96:111], v[150:153], v[130:133], v[96:111]
	ds_read_b128 v[146:149], v193 offset:32768
	ds_read_b128 v[150:153], v193 offset:40960
	ds_read_b64_tr_b16 v[184:185], v206 offset:0x4000
	ds_read_b64_tr_b16 v[186:187], v206 offset:0x4800
	ds_read_b64_tr_b16 v[216:217], v206 offset:0x5000
	ds_read_b64_tr_b16 v[218:219], v206 offset:0x5800
	ds_read_b64_tr_b16 v[220:221], v206 offset:0x6000
	ds_read_b64_tr_b16 v[222:223], v206 offset:0x6800
	ds_read_b64_tr_b16 v[224:225], v206 offset:0x7000
	ds_read_b64_tr_b16 v[226:227], v206 offset:0x7800
	v_permlane32_swap_b32_e32 v81, v83
	v_permlane32_swap_b32_e32 v84, v86
	v_permlane32_swap_b32_e32 v85, v87
	v_permlane32_swap_b32_e32 v88, v90
	v_permlane32_swap_b32_e32 v89, v91
	v_permlane32_swap_b32_e32 v92, v94
	s_waitcnt lgkmcnt(9)
	v_mfma_f32_32x32x16_bf16 v[64:79], v[146:149], v[134:137], v[64:79]
	v_permlane32_swap_b32_e32 v93, v95
	s_waitcnt lgkmcnt(8)
	v_mfma_f32_32x32x16_bf16 v[96:111], v[150:153], v[134:137], v[96:111]
	s_waitcnt vmcnt(0)
	ds_write_b128 v211, v[162:165]
	s_waitcnt lgkmcnt(7)
	v_mfma_f32_32x32x16_bf16 v[0:15], v[80:83], v[184:187], v[0:15]
	ds_read_b64_tr_b16 v[184:185], v206 offset:0x4200
	ds_read_b64_tr_b16 v[186:187], v206 offset:0x4a00
	v_add_co_u32_e32 v150, vcc, s21, v178
	s_nop 1
	v_addc_co_u32_e32 v151, vcc, -1, v179, vcc
	v_add_co_u32_e32 v154, vcc, s22, v178
	s_nop 1
	v_addc_co_u32_e32 v155, vcc, -1, v179, vcc
	s_waitcnt lgkmcnt(7)
	v_mfma_f32_32x32x16_bf16 v[0:15], v[84:87], v[216:219], v[0:15]
	ds_read_b64_tr_b16 v[216:217], v206 offset:0x5200
	ds_read_b64_tr_b16 v[218:219], v206 offset:0x5a00
	global_load_dwordx4 v[146:149], v[150:151], off
	global_load_dwordx4 v[150:153], v[150:151], off offset:-512
	global_load_dwordx4 v[158:161], v[154:155], off
	global_load_dwordx4 v[154:157], v[154:155], off offset:-512
	s_waitcnt lgkmcnt(7)
	v_mfma_f32_32x32x16_bf16 v[0:15], v[88:91], v[220:223], v[0:15]
	ds_read_b64_tr_b16 v[220:221], v206 offset:0x6200
	ds_read_b64_tr_b16 v[222:223], v206 offset:0x6a00
	s_waitcnt lgkmcnt(7)
	v_mfma_f32_32x32x16_bf16 v[0:15], v[92:95], v[224:227], v[0:15]
	ds_read_b64_tr_b16 v[224:225], v206 offset:0x7200
	ds_read_b64_tr_b16 v[226:227], v206 offset:0x7a00
	ds_write_b128 v212, v[174:177]
	s_waitcnt lgkmcnt(7)
	v_mfma_f32_32x32x16_bf16 v[16:31], v[80:83], v[184:187], v[16:31]
	ds_read_b64_tr_b16 v[184:185], v206 offset:0x4400
	ds_read_b64_tr_b16 v[186:187], v206 offset:0x4c00
	s_waitcnt lgkmcnt(7)
	v_mfma_f32_32x32x16_bf16 v[16:31], v[84:87], v[216:219], v[16:31]
	ds_read_b64_tr_b16 v[216:217], v206 offset:0x5400
	ds_read_b64_tr_b16 v[218:219], v206 offset:0x5c00
	s_waitcnt lgkmcnt(7)
	v_mfma_f32_32x32x16_bf16 v[16:31], v[88:91], v[220:223], v[16:31]
	ds_read_b64_tr_b16 v[220:221], v206 offset:0x6400
	ds_read_b64_tr_b16 v[222:223], v206 offset:0x6c00
	s_waitcnt lgkmcnt(7)
	v_mfma_f32_32x32x16_bf16 v[16:31], v[92:95], v[224:227], v[16:31]
	ds_read_b64_tr_b16 v[224:225], v206 offset:0x7400
	ds_read_b64_tr_b16 v[226:227], v206 offset:0x7c00
	ds_write_b128 v213, v[166:169]
	s_waitcnt lgkmcnt(7)
	v_mfma_f32_32x32x16_bf16 v[32:47], v[80:83], v[184:187], v[32:47]
	ds_read_b64_tr_b16 v[184:185], v206 offset:0x4600
	ds_read_b64_tr_b16 v[186:187], v206 offset:0x4e00
	v_exp_f32_e32 v215, v74
	v_exp_f32_e32 v188, v68
	s_waitcnt lgkmcnt(7)
	v_mfma_f32_32x32x16_bf16 v[32:47], v[84:87], v[216:219], v[32:47]
	ds_read_b64_tr_b16 v[216:217], v206 offset:0x5600
	ds_read_b64_tr_b16 v[218:219], v206 offset:0x5e00
	v_exp_f32_e32 v189, v69
	v_exp_f32_e32 v196, v70
	s_waitcnt lgkmcnt(7)
	v_mfma_f32_32x32x16_bf16 v[32:47], v[88:91], v[220:223], v[32:47]
	ds_read_b64_tr_b16 v[220:221], v206 offset:0x6600
	ds_read_b64_tr_b16 v[222:223], v206 offset:0x6e00
	v_exp_f32_e32 v197, v71
	v_exp_f32_e32 v198, v72
	s_waitcnt lgkmcnt(7)
	v_mfma_f32_32x32x16_bf16 v[32:47], v[92:95], v[224:227], v[32:47]
	ds_read_b64_tr_b16 v[224:225], v206 offset:0x7600
	ds_read_b64_tr_b16 v[226:227], v206 offset:0x7e00
	v_exp_f32_e32 v199, v73
	ds_write_b128 v214, v[170:173]
	s_waitcnt lgkmcnt(7)
	v_mfma_f32_32x32x16_bf16 v[48:63], v[80:83], v[184:187], v[48:63]
	v_exp_f32_e32 v184, v64
	v_exp_f32_e32 v185, v65
	v_exp_f32_e32 v186, v66
	v_exp_f32_e32 v187, v67
	s_waitcnt lgkmcnt(5)
	v_mfma_f32_32x32x16_bf16 v[48:63], v[84:87], v[216:219], v[48:63]
	v_exp_f32_e32 v219, v78
	v_exp_f32_e32 v216, v75
	s_waitcnt lgkmcnt(3)
	v_mfma_f32_32x32x16_bf16 v[48:63], v[88:91], v[220:223], v[48:63]
	v_exp_f32_e32 v220, v79
	v_exp_f32_e32 v217, v76
	v_exp_f32_e32 v218, v77
	s_waitcnt lgkmcnt(0)
	s_barrier
; #define SLOAD(i, k0) do { sr_[i].vs0 = ld8(&Vh[(long)((k0) + sr) * LDK + sc]); sr_[i].vs1 = ld8(&Vh[(long)((k0) + 32 + sr) * LDK + sc]); \
;     sr_[i].ks0 = ld8(&Kh[(long)((k0) + sr) * LDK + sc]); sr_[i].ks1 = ld8(&Kh[(long)((k0) + 32 + sr) * LDK + sc]); } while (0)
; #define SWAIT() asm volatile("s_waitcnt vmcnt(4)" ::: "memory")
; #define SWRITE_I(B, i) do { LDSV(wv0 + (B) * 16384) = sr_[i].vs0; LDSV(wv1 + (B) * 16384) = sr_[i].vs1; LDSV(wk0 + (B) * 16384) = sr_[i].ks0; LDSV(wk1 + (B) * 16384) = sr_[i].ks1; } while (0)
; #define NOP_() do { } while (0)
; __device__ __forceinline__ void finishSM(f32x16& p0, f32x16& p1, float alpha, float& l_reg, bf16x8& pa0, bf16x8& pa1, bf16x8& pa2, bf16x8& pa3) {
;   for (int r = 0; r < 16; ++r) p1[r] = __builtin_amdgcn_exp2f(p1[r]);
;   float ps = 0; for (int r = 0; r < 16; ++r) ps += p0[r]; for (int r = 0; r < 16; ++r) ps += p1[r];
;   { auto rr = __builtin_amdgcn_permlane32_swap(__float_as_uint(ps), __float_as_uint(ps), false, false);
;     ps = __uint_as_float(rr[0]) + __uint_as_float(rr[1]); }
;   l_reg = l_reg * alpha + ps;
;     ...
;   PK4(p0, 0, pa0); PK4(p0, 8, pa1); PK4(p1, 0, pa2); PK4(p1, 8, pa3);
;     ...
; }
; template <bool PARTIAL, bool FIXED> ...
;     ...
;   int j = 1;
;   for (; j + 6 < NT; j += 6) {
;     HALF_B(1, 0, SLOAD(1, (j + 2) * KVBLK), do { SWAIT(); SWRITE_I(2, 0); } while (0));
;     HALF_A(2, 1, NOP_(), SLOAD(0, (j + 3) * KVBLK), do { SWAIT(); SWRITE_I(0, 1); } while (0));
;     HALF_B(0, 2, SLOAD(1, (j + 4) * KVBLK), do { SWAIT(); SWRITE_I(1, 0); } while (0));
	v_mfma_f32_32x32x16_bf16 v[48:63], v[92:95], v[224:227], v[48:63]
	ds_read_b128 v[64:67], v207
	ds_read_b128 v[68:71], v207 offset:8192
	ds_read_b128 v[162:165], v208
	ds_read_b128 v[166:169], v208 offset:8192
	v_exp_f32_e32 v170, v104
	v_exp_f32_e32 v171, v105
	v_exp_f32_e32 v172, v106
	v_exp_f32_e32 v173, v107
	v_exp_f32_e32 v174, v108
	v_exp_f32_e32 v175, v109
	v_exp_f32_e32 v176, v110
	v_exp_f32_e32 v111, v111
	s_waitcnt lgkmcnt(3)
	v_mfma_f32_32x32x16_bf16 v[80:95], v[64:67], v[142:145], 0
	v_exp_f32_e32 v236, v96
	v_add_f32_e32 v96, 0, v184
	v_add_f32_e32 v96, v185, v96
	v_add_f32_e32 v96, v186, v96
	s_waitcnt lgkmcnt(2)
	v_mfma_f32_32x32x16_bf16 v[64:79], v[68:71], v[142:145], 0
	v_add_f32_e32 v96, v187, v96
	v_add_f32_e32 v96, v188, v96
	v_add_f32_e32 v96, v189, v96
	s_waitcnt lgkmcnt(1)
	v_mfma_f32_32x32x16_bf16 v[80:95], v[162:165], v[138:141], v[80:95]
	v_add_f32_e32 v96, v196, v96
	v_add_f32_e32 v96, v197, v96
	v_add_f32_e32 v96, v198, v96
	s_waitcnt lgkmcnt(0)
	v_mfma_f32_32x32x16_bf16 v[64:79], v[166:169], v[138:141], v[64:79]
	ds_read_b128 v[162:165], v209
	ds_read_b128 v[166:169], v209 offset:8192
	v_add_f32_e32 v96, v199, v96
	v_add_f32_e32 v96, v215, v96
	v_add_f32_e32 v96, v216, v96
	v_add_f32_e32 v96, v217, v96
	v_exp_f32_e32 v237, v97
	s_waitcnt lgkmcnt(1)
	v_mfma_f32_32x32x16_bf16 v[80:95], v[162:165], v[112:115], v[80:95]
	v_add_f32_e32 v96, v218, v96
	v_exp_f32_e32 v238, v98
	v_add_f32_e32 v96, v219, v96
	v_exp_f32_e32 v239, v99
	s_waitcnt lgkmcnt(0)
	v_mfma_f32_32x32x16_bf16 v[64:79], v[166:169], v[112:115], v[64:79]
	ds_read_b128 v[162:165], v210
	ds_read_b128 v[166:169], v210 offset:8192
	v_add_f32_e32 v96, v220, v96
	v_exp_f32_e32 v247, v100
	v_add_f32_e32 v96, v236, v96
	v_exp_f32_e32 v248, v101
	s_waitcnt lgkmcnt(1)
	v_mfma_f32_32x32x16_bf16 v[80:95], v[162:165], v[116:119], v[80:95]
	v_add_f32_e32 v96, v237, v96
	v_exp_f32_e32 v249, v102
	v_add_f32_e32 v96, v238, v96
	v_exp_f32_e32 v252, v103
	s_waitcnt lgkmcnt(0)
	v_mfma_f32_32x32x16_bf16 v[64:79], v[166:169], v[116:119], v[64:79]
	ds_read_b128 v[162:165], v190 offset:0
	ds_read_b128 v[166:169], v190 offset:8192
	v_add_f32_e32 v96, v239, v96
	v_add_f32_e32 v96, v247, v96
	v_add_f32_e32 v96, v248, v96
	v_add_f32_e32 v96, v249, v96
	v_add_f32_e32 v96, v252, v96
	v_add_f32_e32 v96, v170, v96
	s_waitcnt lgkmcnt(1)
	v_mfma_f32_32x32x16_bf16 v[80:95], v[162:165], v[120:123], v[80:95]
	v_add_f32_e32 v96, v171, v96
	v_add_f32_e32 v96, v172, v96
	v_add_f32_e32 v96, v173, v96
	v_add_f32_e32 v96, v174, v96
	v_add_f32_e32 v96, v175, v96
	s_waitcnt lgkmcnt(0)
	v_mfma_f32_32x32x16_bf16 v[64:79], v[166:169], v[120:123], v[64:79]
	ds_read_b128 v[162:165], v191 offset:0
	ds_read_b128 v[166:169], v191 offset:8192
	v_add_f32_e32 v96, v176, v96
	v_add_f32_e32 v181, v111, v96
	v_mov_b32_e32 v183, v181
	s_nop 1
	v_permlane32_swap_b32_e32 v181, v183
	v_pk_add_f32 v[96:97], v[180:181], v[182:183]
	s_waitcnt lgkmcnt(1)
	v_mfma_f32_32x32x16_bf16 v[80:95], v[162:165], v[124:127], v[80:95]
	s_nop 0
	v_add_f32_e32 v96, v128, v96
	v_add_f32_e32 v128, v96, v97
	v_cvt_pk_bf16_f32 v96, v184, v185
	v_cvt_pk_bf16_f32 v97, v186, v187
	s_waitcnt lgkmcnt(0)
	v_mfma_f32_32x32x16_bf16 v[64:79], v[166:169], v[124:127], v[64:79]
	ds_read_b128 v[162:165], v192 offset:0
	ds_read_b128 v[166:169], v192 offset:8192
	v_cvt_pk_bf16_f32 v98, v188, v189
	v_cvt_pk_bf16_f32 v99, v196, v197
	v_cvt_pk_bf16_f32 v100, v198, v199
	v_cvt_pk_bf16_f32 v101, v215, v216
	v_cvt_pk_bf16_f32 v102, v217, v218
	v_cvt_pk_bf16_f32 v103, v219, v220
	s_waitcnt lgkmcnt(1)
	v_mfma_f32_32x32x16_bf16 v[80:95], v[162:165], v[130:133], v[80:95]
	v_cvt_pk_bf16_f32 v104, v236, v237
	v_cvt_pk_bf16_f32 v105, v238, v239
	v_cvt_pk_bf16_f32 v106, v247, v248
	v_cvt_pk_bf16_f32 v107, v249, v252
	v_cvt_pk_bf16_f32 v108, v170, v171
	s_waitcnt lgkmcnt(0)
	v_mfma_f32_32x32x16_bf16 v[64:79], v[166:169], v[130:133], v[64:79]
	ds_read_b128 v[162:165], v193 offset:0
	ds_read_b128 v[166:169], v193 offset:8192
	ds_read_b64_tr_b16 v[180:181], v206 offset:0x8000
	ds_read_b64_tr_b16 v[182:183], v206 offset:0x8800
	ds_read_b64_tr_b16 v[184:185], v206 offset:0x9000
	ds_read_b64_tr_b16 v[186:187], v206 offset:0x9800
	ds_read_b64_tr_b16 v[216:217], v206 offset:0xa000
	ds_read_b64_tr_b16 v[218:219], v206 offset:0xa800
	ds_read_b64_tr_b16 v[220:221], v206 offset:0xb000
	ds_read_b64_tr_b16 v[222:223], v206 offset:0xb800
	v_cvt_pk_bf16_f32 v109, v172, v173
	v_cvt_pk_bf16_f32 v110, v174, v175
	v_cvt_pk_bf16_f32 v111, v176, v111
	s_nop 0
	v_permlane32_swap_b32_e32 v96, v98
	v_permlane32_swap_b32_e32 v97, v99
	s_waitcnt lgkmcnt(9)
	v_mfma_f32_32x32x16_bf16 v[80:95], v[162:165], v[134:137], v[80:95]
	v_permlane32_swap_b32_e32 v100, v102
	v_permlane32_swap_b32_e32 v101, v103
	v_permlane32_swap_b32_e32 v104, v106
	v_permlane32_swap_b32_e32 v105, v107
	v_permlane32_swap_b32_e32 v108, v110
	s_waitcnt lgkmcnt(8)
	v_mfma_f32_32x32x16_bf16 v[64:79], v[166:169], v[134:137], v[64:79]
	v_permlane32_swap_b32_e32 v109, v111
	s_waitcnt vmcnt(0)
	ds_write_b128 v211, v[146:149] offset:16384
	s_waitcnt lgkmcnt(7)
	v_mfma_f32_32x32x16_bf16 v[0:15], v[96:99], v[180:183], v[0:15]
	ds_read_b64_tr_b16 v[180:181], v206 offset:0x8200
	ds_read_b64_tr_b16 v[182:183], v206 offset:0x8a00
	v_add_co_u32_e32 v166, vcc, s23, v178
	s_nop 1
	v_addc_co_u32_e32 v167, vcc, -1, v179, vcc
	v_add_co_u32_e32 v170, vcc, s24, v178
	s_nop 1
	v_addc_co_u32_e32 v171, vcc, -1, v179, vcc
	s_waitcnt lgkmcnt(7)
; #define SLOAD(i, k0) do { sr_[i].vs0 = ld8(&Vh[(long)((k0) + sr) * LDK + sc]); sr_[i].vs1 = ld8(&Vh[(long)((k0) + 32 + sr) * LDK + sc]); \
;     sr_[i].ks0 = ld8(&Kh[(long)((k0) + sr) * LDK + sc]); sr_[i].ks1 = ld8(&Kh[(long)((k0) + 32 + sr) * LDK + sc]); } while (0)
; #define SWAIT() asm volatile("s_waitcnt vmcnt(4)" ::: "memory")
; #define SWRITE_I(B, i) do { LDSV(wv0 + (B) * 16384) = sr_[i].vs0; LDSV(wv1 + (B) * 16384) = sr_[i].vs1; LDSV(wk0 + (B) * 16384) = sr_[i].ks0; LDSV(wk1 + (B) * 16384) = sr_[i].ks1; } while (0)
; #define NOP_() do { } while (0)
; template <int BOFF> __device__ __forceinline__ void qkt_i(f32x16& p0, f32x16& p1, const int (&kb)[4], const bf16x8* qr) {
;   p0 = f32x16{}; p1 = f32x16{};
; #pragma unroll
;   for (int d0 = 0; d0 < 8; ++d0) { const int off = BOFF + (d0 >> 2) * 128;
;     const bf16x8 b0 = LDSV(kb[d0 & 3] + off), b1 = LDSV(kb[d0 & 3] + off + 8192);
;     p0 = __builtin_amdgcn_mfma_f32_32x32x16_bf16(b0, qr[d0], p0, 0, 0, 0);
;     p1 = __builtin_amdgcn_mfma_f32_32x32x16_bf16(b1, qr[d0], p1, 0, 0, 0); }
; }
; template <bool PARTIAL, bool FIXED> ...
;     ...
;   int j = 1;
;   for (; j + 6 < NT; j += 6) {
;     HALF_B(1, 0, SLOAD(1, (j + 2) * KVBLK), do { SWAIT(); SWRITE_I(2, 0); } while (0));
;     HALF_A(2, 1, NOP_(), SLOAD(0, (j + 3) * KVBLK), do { SWAIT(); SWRITE_I(0, 1); } while (0));
;     HALF_B(0, 2, SLOAD(1, (j + 4) * KVBLK), do { SWAIT(); SWRITE_I(1, 0); } while (0));
;     HALF_A(1, 0, NOP_(), SLOAD(0, (j + 5) * KVBLK), do { SWAIT(); SWRITE_I(2, 1); } while (0));
	v_mfma_f32_32x32x16_bf16 v[0:15], v[100:103], v[184:187], v[0:15]
	ds_read_b64_tr_b16 v[184:185], v206 offset:0x9200
	ds_read_b64_tr_b16 v[186:187], v206 offset:0x9a00
	global_load_dwordx4 v[162:165], v[166:167], off
	global_load_dwordx4 v[166:169], v[166:167], off offset:-512
	global_load_dwordx4 v[174:177], v[170:171], off
	global_load_dwordx4 v[170:173], v[170:171], off offset:-512
	s_waitcnt lgkmcnt(7)
	v_mfma_f32_32x32x16_bf16 v[0:15], v[104:107], v[216:219], v[0:15]
	ds_read_b64_tr_b16 v[216:217], v206 offset:0xa200
	ds_read_b64_tr_b16 v[218:219], v206 offset:0xaa00
	s_waitcnt lgkmcnt(7)
	v_mfma_f32_32x32x16_bf16 v[0:15], v[108:111], v[220:223], v[0:15]
	ds_read_b64_tr_b16 v[220:221], v206 offset:0xb200
	ds_read_b64_tr_b16 v[222:223], v206 offset:0xba00
	ds_write_b128 v212, v[158:161] offset:16384
	s_waitcnt lgkmcnt(7)
	v_mfma_f32_32x32x16_bf16 v[16:31], v[96:99], v[180:183], v[16:31]
	ds_read_b64_tr_b16 v[180:181], v206 offset:0x8400
	ds_read_b64_tr_b16 v[182:183], v206 offset:0x8c00
	s_waitcnt lgkmcnt(7)
	v_mfma_f32_32x32x16_bf16 v[16:31], v[100:103], v[184:187], v[16:31]
	ds_read_b64_tr_b16 v[184:185], v206 offset:0x9400
	ds_read_b64_tr_b16 v[186:187], v206 offset:0x9c00
	s_waitcnt lgkmcnt(7)
	v_mfma_f32_32x32x16_bf16 v[16:31], v[104:107], v[216:219], v[16:31]
	ds_read_b64_tr_b16 v[216:217], v206 offset:0xa400
	ds_read_b64_tr_b16 v[218:219], v206 offset:0xac00
	s_waitcnt lgkmcnt(7)
	v_mfma_f32_32x32x16_bf16 v[16:31], v[108:111], v[220:223], v[16:31]
	ds_read_b64_tr_b16 v[220:221], v206 offset:0xb400
	ds_read_b64_tr_b16 v[222:223], v206 offset:0xbc00
	ds_write_b128 v213, v[150:153] offset:16384
	s_waitcnt lgkmcnt(7)
	v_mfma_f32_32x32x16_bf16 v[32:47], v[96:99], v[180:183], v[32:47]
	ds_read_b64_tr_b16 v[180:181], v206 offset:0x8600
	ds_read_b64_tr_b16 v[182:183], v206 offset:0x8e00
	v_exp_f32_e32 v215, v92
	v_exp_f32_e32 v188, v86
	s_waitcnt lgkmcnt(7)
	v_mfma_f32_32x32x16_bf16 v[32:47], v[100:103], v[184:187], v[32:47]
	ds_read_b64_tr_b16 v[184:185], v206 offset:0x9600
	ds_read_b64_tr_b16 v[186:187], v206 offset:0x9e00
	v_exp_f32_e32 v189, v87
	v_exp_f32_e32 v196, v88
	s_waitcnt lgkmcnt(7)
	v_mfma_f32_32x32x16_bf16 v[32:47], v[104:107], v[216:219], v[32:47]
	ds_read_b64_tr_b16 v[216:217], v206 offset:0xa600
	ds_read_b64_tr_b16 v[218:219], v206 offset:0xae00
	v_exp_f32_e32 v197, v89
	v_exp_f32_e32 v198, v90
	s_waitcnt lgkmcnt(7)
	v_mfma_f32_32x32x16_bf16 v[32:47], v[108:111], v[220:223], v[32:47]
	ds_read_b64_tr_b16 v[220:221], v206 offset:0xb600
	ds_read_b64_tr_b16 v[222:223], v206 offset:0xbe00
	v_exp_f32_e32 v199, v91
	ds_write_b128 v214, v[154:157] offset:16384
	s_waitcnt lgkmcnt(7)
	v_mfma_f32_32x32x16_bf16 v[48:63], v[96:99], v[180:183], v[48:63]
	v_exp_f32_e32 v181, v80
	v_exp_f32_e32 v183, v81
	s_waitcnt lgkmcnt(5)
	v_mfma_f32_32x32x16_bf16 v[48:63], v[100:103], v[184:187], v[48:63]
	v_exp_f32_e32 v184, v82
	v_exp_f32_e32 v185, v83
	v_exp_f32_e32 v186, v84
	v_exp_f32_e32 v187, v85
	s_waitcnt lgkmcnt(3)
	v_mfma_f32_32x32x16_bf16 v[48:63], v[104:107], v[216:219], v[48:63]
	v_exp_f32_e32 v216, v93
	v_exp_f32_e32 v217, v94
	v_exp_f32_e32 v218, v95
	s_waitcnt lgkmcnt(0)
	s_barrier
	v_mfma_f32_32x32x16_bf16 v[48:63], v[108:111], v[220:223], v[48:63]
	ds_read_b128 v[80:83], v207 offset:16384
	ds_read_b128 v[96:99], v207 offset:24576
	ds_read_b128 v[146:149], v208 offset:16384
	ds_read_b128 v[150:153], v208 offset:24576
	v_exp_f32_e32 v154, v72
	v_exp_f32_e32 v155, v73
	v_exp_f32_e32 v156, v74
	v_exp_f32_e32 v157, v75
	v_exp_f32_e32 v158, v76
	v_exp_f32_e32 v159, v77
	v_exp_f32_e32 v160, v78
	v_exp_f32_e32 v79, v79
	s_waitcnt lgkmcnt(3)
	v_mfma_f32_32x32x16_bf16 v[80:95], v[80:83], v[142:145], 0
	v_exp_f32_e32 v236, v64
	v_add_f32_e32 v64, 0, v181
	v_add_f32_e32 v64, v183, v64
	v_add_f32_e32 v64, v184, v64
	s_waitcnt lgkmcnt(2)
	v_mfma_f32_32x32x16_bf16 v[96:111], v[96:99], v[142:145], 0
	v_add_f32_e32 v64, v185, v64
	v_add_f32_e32 v64, v186, v64
	v_add_f32_e32 v64, v187, v64
	s_waitcnt lgkmcnt(1)
	v_mfma_f32_32x32x16_bf16 v[80:95], v[146:149], v[138:141], v[80:95]
	v_add_f32_e32 v64, v188, v64
	v_add_f32_e32 v64, v189, v64
	v_add_f32_e32 v64, v196, v64
	s_waitcnt lgkmcnt(0)
	v_mfma_f32_32x32x16_bf16 v[96:111], v[150:153], v[138:141], v[96:111]
	ds_read_b128 v[146:149], v209 offset:16384
	ds_read_b128 v[150:153], v209 offset:24576
	v_add_f32_e32 v64, v197, v64
	v_add_f32_e32 v64, v198, v64
	v_add_f32_e32 v64, v199, v64
	v_add_f32_e32 v64, v215, v64
	v_exp_f32_e32 v237, v65
	s_waitcnt lgkmcnt(1)
	v_mfma_f32_32x32x16_bf16 v[80:95], v[146:149], v[112:115], v[80:95]
	v_add_f32_e32 v64, v216, v64
	v_exp_f32_e32 v238, v66
	v_add_f32_e32 v64, v217, v64
	v_exp_f32_e32 v239, v67
	s_waitcnt lgkmcnt(0)
	v_mfma_f32_32x32x16_bf16 v[96:111], v[150:153], v[112:115], v[96:111]
	ds_read_b128 v[146:149], v210 offset:16384
	ds_read_b128 v[150:153], v210 offset:24576
	v_add_f32_e32 v64, v218, v64
	v_exp_f32_e32 v247, v68
	v_add_f32_e32 v64, v236, v64
	v_exp_f32_e32 v248, v69
	s_waitcnt lgkmcnt(1)
	v_mfma_f32_32x32x16_bf16 v[80:95], v[146:149], v[116:119], v[80:95]
	v_add_f32_e32 v64, v237, v64
	v_exp_f32_e32 v249, v70
	v_add_f32_e32 v64, v238, v64
	v_exp_f32_e32 v252, v71
	s_waitcnt lgkmcnt(0)
	v_mfma_f32_32x32x16_bf16 v[96:111], v[150:153], v[116:119], v[96:111]
	ds_read_b128 v[146:149], v190 offset:16384
	ds_read_b128 v[150:153], v190 offset:24576
	v_add_f32_e32 v64, v239, v64
	v_add_f32_e32 v64, v247, v64
	v_add_f32_e32 v64, v248, v64
	v_add_f32_e32 v64, v249, v64
	v_add_f32_e32 v64, v252, v64
	v_add_f32_e32 v64, v154, v64
	s_waitcnt lgkmcnt(1)
; #define SBAR() __builtin_amdgcn_sched_barrier(0)
; #define SLOAD(i, k0) do { sr_[i].vs0 = ld8(&Vh[(long)((k0) + sr) * LDK + sc]); sr_[i].vs1 = ld8(&Vh[(long)((k0) + 32 + sr) * LDK + sc]); \
;     sr_[i].ks0 = ld8(&Kh[(long)((k0) + sr) * LDK + sc]); sr_[i].ks1 = ld8(&Kh[(long)((k0) + 32 + sr) * LDK + sc]); } while (0)
; #define SWAIT() asm volatile("s_waitcnt vmcnt(4)" ::: "memory")
; #define SWRITE_I(B, i) do { LDSV(wv0 + (B) * 16384) = sr_[i].vs0; LDSV(wv1 + (B) * 16384) = sr_[i].vs1; LDSV(wk0 + (B) * 16384) = sr_[i].ks0; LDSV(wk1 + (B) * 16384) = sr_[i].ks1; } while (0)
; #define NOP_() do { } while (0)
; template <int D0, int BOFF> __device__ __forceinline__ void pv_one_i(f32x16& od, int vb, bf16x8 pa0, bf16x8 pa1, bf16x8 pa2, bf16x8 pa3) {
;   const s16x4 l0 = tr_read<BOFF + v_rd_off(D0, 0, 0)>(vb), h0 = tr_read<BOFF + v_rd_off(D0, 0, 1)>(vb), l1 = tr_read<BOFF + v_rd_off(D0, 1, 0)>(vb), h1 = tr_read<BOFF + v_rd_off(D0, 1, 1)>(vb);
;   const s16x4 l2 = tr_read<BOFF + v_rd_off(D0, 2, 0)>(vb), h2 = tr_read<BOFF + v_rd_off(D0, 2, 1)>(vb), l3 = tr_read<BOFF + v_rd_off(D0, 3, 0)>(vb), h3 = tr_read<BOFF + v_rd_off(D0, 3, 1)>(vb);
;   asm volatile("s_waitcnt lgkmcnt(0)" ::: "memory"); SBAR();
;     ...
;   od = __builtin_amdgcn_mfma_f32_32x32x16_bf16(pa0, PK(l0, h0), od, 0, 0, 0);
;   od = __builtin_amdgcn_mfma_f32_32x32x16_bf16(pa1, PK(l1, h1), od, 0, 0, 0);
;   od = __builtin_amdgcn_mfma_f32_32x32x16_bf16(pa2, PK(l2, h2), od, 0, 0, 0);
;   od = __builtin_amdgcn_mfma_f32_32x32x16_bf16(pa3, PK(l3, h3), od, 0, 0, 0);
;     ...
; }
; template <int BOFF> __device__ __forceinline__ void pv_i(f32x16* o, int vb, bf16x8 pa0, bf16x8 pa1, bf16x8 pa2, bf16x8 pa3) {
;   pv_one_i<0, BOFF>(o[0], vb, pa0, pa1, pa2, pa3); pv_one_i<1, BOFF>(o[1], vb, pa0, pa1, pa2, pa3); pv_one_i<2, BOFF>(o[2], vb, pa0, pa1, pa2, pa3); pv_one_i<3, BOFF>(o[3], vb, pa0, pa1, pa2, pa3);
; template <bool PARTIAL, bool FIXED> ...
;     ...
;   int j = 1;
;   for (; j + 6 < NT; j += 6) {
;     HALF_B(1, 0, SLOAD(1, (j + 2) * KVBLK), do { SWAIT(); SWRITE_I(2, 0); } while (0));
;     HALF_A(2, 1, NOP_(), SLOAD(0, (j + 3) * KVBLK), do { SWAIT(); SWRITE_I(0, 1); } while (0));
;     HALF_B(0, 2, SLOAD(1, (j + 4) * KVBLK), do { SWAIT(); SWRITE_I(1, 0); } while (0));
;     HALF_A(1, 0, NOP_(), SLOAD(0, (j + 5) * KVBLK), do { SWAIT(); SWRITE_I(2, 1); } while (0));
	v_mfma_f32_32x32x16_bf16 v[80:95], v[146:149], v[120:123], v[80:95]
	v_add_f32_e32 v64, v155, v64
	v_add_f32_e32 v64, v156, v64
	v_add_f32_e32 v64, v157, v64
	v_add_f32_e32 v64, v158, v64
	v_add_f32_e32 v64, v159, v64
	s_waitcnt lgkmcnt(0)
	v_mfma_f32_32x32x16_bf16 v[96:111], v[150:153], v[120:123], v[96:111]
	ds_read_b128 v[146:149], v191 offset:16384
	ds_read_b128 v[150:153], v191 offset:24576
	v_add_f32_e32 v64, v160, v64
	v_add_f32_e32 v180, v79, v64
	v_cvt_pk_bf16_f32 v64, v181, v183
	v_cvt_pk_bf16_f32 v65, v184, v185
	v_cvt_pk_bf16_f32 v66, v186, v187
	v_cvt_pk_bf16_f32 v67, v188, v189
	s_waitcnt lgkmcnt(1)
	v_mfma_f32_32x32x16_bf16 v[80:95], v[146:149], v[124:127], v[80:95]
	v_cvt_pk_bf16_f32 v68, v196, v197
	v_cvt_pk_bf16_f32 v69, v198, v199
	v_cvt_pk_bf16_f32 v70, v215, v216
	v_cvt_pk_bf16_f32 v71, v217, v218
	v_cvt_pk_bf16_f32 v72, v236, v237
	s_waitcnt lgkmcnt(0)
	v_mfma_f32_32x32x16_bf16 v[96:111], v[150:153], v[124:127], v[96:111]
	ds_read_b128 v[146:149], v192 offset:16384
	ds_read_b128 v[150:153], v192 offset:24576
	v_cvt_pk_bf16_f32 v73, v238, v239
	v_cvt_pk_bf16_f32 v74, v247, v248
	v_cvt_pk_bf16_f32 v75, v249, v252
	v_cvt_pk_bf16_f32 v76, v154, v155
	v_cvt_pk_bf16_f32 v77, v156, v157
	v_cvt_pk_bf16_f32 v78, v158, v159
	s_waitcnt lgkmcnt(1)
	v_mfma_f32_32x32x16_bf16 v[80:95], v[146:149], v[130:133], v[80:95]
	v_cvt_pk_bf16_f32 v79, v160, v79
	v_mov_b32_e32 v182, v180
	v_permlane32_swap_b32_e32 v64, v66
	v_permlane32_swap_b32_e32 v65, v67
	v_permlane32_swap_b32_e32 v68, v70
	s_waitcnt lgkmcnt(0)
	v_mfma_f32_32x32x16_bf16 v[96:111], v[150:153], v[130:133], v[96:111]
	ds_read_b128 v[146:149], v193 offset:16384
	ds_read_b128 v[150:153], v193 offset:24576
	ds_read_b64_tr_b16 v[184:185], v206 offset:0
	ds_read_b64_tr_b16 v[186:187], v206 offset:0x800
	ds_read_b64_tr_b16 v[216:217], v206 offset:0x1000
	ds_read_b64_tr_b16 v[218:219], v206 offset:0x1800
	ds_read_b64_tr_b16 v[220:221], v206 offset:0x2000
	ds_read_b64_tr_b16 v[222:223], v206 offset:0x2800
	ds_read_b64_tr_b16 v[224:225], v206 offset:0x3000
	ds_read_b64_tr_b16 v[226:227], v206 offset:0x3800
	v_permlane32_swap_b32_e32 v69, v71
	v_permlane32_swap_b32_e32 v72, v74
	v_permlane32_swap_b32_e32 v73, v75
	v_permlane32_swap_b32_e32 v76, v78
	v_permlane32_swap_b32_e32 v77, v79
	v_permlane32_swap_b32_e32 v180, v182
	s_waitcnt lgkmcnt(9)
	v_mfma_f32_32x32x16_bf16 v[80:95], v[146:149], v[134:137], v[80:95]
	s_waitcnt lgkmcnt(8)
	v_mfma_f32_32x32x16_bf16 v[96:111], v[150:153], v[134:137], v[96:111]
	s_waitcnt vmcnt(0)
	ds_write_b128 v211, v[162:165] offset:32768
	s_waitcnt lgkmcnt(7)
	v_mfma_f32_32x32x16_bf16 v[0:15], v[64:67], v[184:187], v[0:15]
	ds_read_b64_tr_b16 v[184:185], v206 offset:0x200
	ds_read_b64_tr_b16 v[186:187], v206 offset:0xa00
	v_add_co_u32_e32 v150, vcc, s25, v178
	s_nop 1
	v_addc_co_u32_e32 v151, vcc, -1, v179, vcc
	v_add_co_u32_e32 v154, vcc, s45, v178
	s_nop 1
	v_addc_co_u32_e32 v155, vcc, -1, v179, vcc
	s_waitcnt lgkmcnt(7)
	v_mfma_f32_32x32x16_bf16 v[0:15], v[68:71], v[216:219], v[0:15]
	ds_read_b64_tr_b16 v[216:217], v206 offset:0x1200
	ds_read_b64_tr_b16 v[218:219], v206 offset:0x1a00
	global_load_dwordx4 v[146:149], v[150:151], off
	global_load_dwordx4 v[150:153], v[150:151], off offset:-512
	global_load_dwordx4 v[158:161], v[154:155], off
	global_load_dwordx4 v[154:157], v[154:155], off offset:-512
	s_waitcnt lgkmcnt(7)
	v_mfma_f32_32x32x16_bf16 v[0:15], v[72:75], v[220:223], v[0:15]
	ds_read_b64_tr_b16 v[220:221], v206 offset:0x2200
	ds_read_b64_tr_b16 v[222:223], v206 offset:0x2a00
	s_waitcnt lgkmcnt(7)
	v_mfma_f32_32x32x16_bf16 v[0:15], v[76:79], v[224:227], v[0:15]
	ds_read_b64_tr_b16 v[224:225], v206 offset:0x3200
	ds_read_b64_tr_b16 v[226:227], v206 offset:0x3a00
	ds_write_b128 v212, v[174:177] offset:32768
	s_waitcnt lgkmcnt(7)
	v_mfma_f32_32x32x16_bf16 v[16:31], v[64:67], v[184:187], v[16:31]
	ds_read_b64_tr_b16 v[184:185], v206 offset:0x400
	ds_read_b64_tr_b16 v[186:187], v206 offset:0xc00
	s_waitcnt lgkmcnt(7)
	v_mfma_f32_32x32x16_bf16 v[16:31], v[68:71], v[216:219], v[16:31]
	ds_read_b64_tr_b16 v[216:217], v206 offset:0x1400
	ds_read_b64_tr_b16 v[218:219], v206 offset:0x1c00
	s_waitcnt lgkmcnt(7)
	v_mfma_f32_32x32x16_bf16 v[16:31], v[72:75], v[220:223], v[16:31]
	ds_read_b64_tr_b16 v[220:221], v206 offset:0x2400
	ds_read_b64_tr_b16 v[222:223], v206 offset:0x2c00
	s_waitcnt lgkmcnt(7)
	v_mfma_f32_32x32x16_bf16 v[16:31], v[76:79], v[224:227], v[16:31]
	ds_read_b64_tr_b16 v[224:225], v206 offset:0x3400
	ds_read_b64_tr_b16 v[226:227], v206 offset:0x3c00
	ds_write_b128 v213, v[166:169] offset:32768
	s_waitcnt lgkmcnt(7)
	v_mfma_f32_32x32x16_bf16 v[32:47], v[64:67], v[184:187], v[32:47]
	ds_read_b64_tr_b16 v[184:185], v206 offset:0x600
	ds_read_b64_tr_b16 v[186:187], v206 offset:0xe00
	v_exp_f32_e32 v215, v90
	v_exp_f32_e32 v188, v84
	s_waitcnt lgkmcnt(7)
	v_mfma_f32_32x32x16_bf16 v[32:47], v[68:71], v[216:219], v[32:47]
	ds_read_b64_tr_b16 v[216:217], v206 offset:0x1600
	ds_read_b64_tr_b16 v[218:219], v206 offset:0x1e00
	v_exp_f32_e32 v189, v85
	v_exp_f32_e32 v196, v86
	s_waitcnt lgkmcnt(7)
	v_mfma_f32_32x32x16_bf16 v[32:47], v[72:75], v[220:223], v[32:47]
	ds_read_b64_tr_b16 v[220:221], v206 offset:0x2600
	ds_read_b64_tr_b16 v[222:223], v206 offset:0x2e00
	v_exp_f32_e32 v197, v87
	v_exp_f32_e32 v198, v88
	s_waitcnt lgkmcnt(7)
	v_mfma_f32_32x32x16_bf16 v[32:47], v[76:79], v[224:227], v[32:47]
	ds_read_b64_tr_b16 v[224:225], v206 offset:0x3600
	ds_read_b64_tr_b16 v[226:227], v206 offset:0x3e00
	v_exp_f32_e32 v199, v89
	ds_write_b128 v214, v[170:173] offset:32768
	s_waitcnt lgkmcnt(7)
	v_mfma_f32_32x32x16_bf16 v[48:63], v[64:67], v[184:187], v[48:63]
	v_exp_f32_e32 v184, v80
	v_exp_f32_e32 v185, v81
	v_exp_f32_e32 v186, v82
	v_exp_f32_e32 v187, v83
	s_waitcnt lgkmcnt(5)
	v_mfma_f32_32x32x16_bf16 v[48:63], v[68:71], v[216:219], v[48:63]
	v_exp_f32_e32 v219, v94
	v_exp_f32_e32 v216, v91
	s_waitcnt lgkmcnt(3)
	v_mfma_f32_32x32x16_bf16 v[48:63], v[72:75], v[220:223], v[48:63]
	v_exp_f32_e32 v220, v95
	v_exp_f32_e32 v217, v92
	v_exp_f32_e32 v218, v93
	s_waitcnt lgkmcnt(0)
	s_barrier
; #define SLOAD(i, k0) do { sr_[i].vs0 = ld8(&Vh[(long)((k0) + sr) * LDK + sc]); sr_[i].vs1 = ld8(&Vh[(long)((k0) + 32 + sr) * LDK + sc]); \
;     sr_[i].ks0 = ld8(&Kh[(long)((k0) + sr) * LDK + sc]); sr_[i].ks1 = ld8(&Kh[(long)((k0) + 32 + sr) * LDK + sc]); } while (0)
; #define SWAIT() asm volatile("s_waitcnt vmcnt(4)" ::: "memory")
; #define SWRITE_I(B, i) do { LDSV(wv0 + (B) * 16384) = sr_[i].vs0; LDSV(wv1 + (B) * 16384) = sr_[i].vs1; LDSV(wk0 + (B) * 16384) = sr_[i].ks0; LDSV(wk1 + (B) * 16384) = sr_[i].ks1; } while (0)
; #define NOP_() do { } while (0)
; __device__ __forceinline__ void finishSM(f32x16& p0, f32x16& p1, float alpha, float& l_reg, bf16x8& pa0, bf16x8& pa1, bf16x8& pa2, bf16x8& pa3) {
;   for (int r = 0; r < 16; ++r) p1[r] = __builtin_amdgcn_exp2f(p1[r]);
;   float ps = 0; for (int r = 0; r < 16; ++r) ps += p0[r]; for (int r = 0; r < 16; ++r) ps += p1[r];
;   { auto rr = __builtin_amdgcn_permlane32_swap(__float_as_uint(ps), __float_as_uint(ps), false, false);
;     ps = __uint_as_float(rr[0]) + __uint_as_float(rr[1]); }
;   l_reg = l_reg * alpha + ps;
;     ...
;   PK4(p0, 0, pa0); PK4(p0, 8, pa1); PK4(p1, 0, pa2); PK4(p1, 8, pa3);
;     ...
; }
; template <bool PARTIAL, bool FIXED> ...
;     ...
;   int j = 1;
;   for (; j + 6 < NT; j += 6) {
;     HALF_B(1, 0, SLOAD(1, (j + 2) * KVBLK), do { SWAIT(); SWRITE_I(2, 0); } while (0));
;     HALF_A(2, 1, NOP_(), SLOAD(0, (j + 3) * KVBLK), do { SWAIT(); SWRITE_I(0, 1); } while (0));
;     HALF_B(0, 2, SLOAD(1, (j + 4) * KVBLK), do { SWAIT(); SWRITE_I(1, 0); } while (0));
;     HALF_A(1, 0, NOP_(), SLOAD(0, (j + 5) * KVBLK), do { SWAIT(); SWRITE_I(2, 1); } while (0));
;     HALF_B(2, 1, SLOAD(1, (j + 6) * KVBLK), do { SWAIT(); SWRITE_I(0, 0); } while (0));
	v_mfma_f32_32x32x16_bf16 v[48:63], v[76:79], v[224:227], v[48:63]
	ds_read_b128 v[64:67], v207 offset:32768
	ds_read_b128 v[80:83], v207 offset:40960
	ds_read_b128 v[162:165], v208 offset:32768
	ds_read_b128 v[166:169], v208 offset:40960
	v_exp_f32_e32 v170, v104
	v_exp_f32_e32 v171, v105
	v_exp_f32_e32 v172, v106
	v_exp_f32_e32 v173, v107
	v_exp_f32_e32 v174, v108
	v_exp_f32_e32 v175, v109
	v_exp_f32_e32 v176, v110
	v_exp_f32_e32 v111, v111
	s_waitcnt lgkmcnt(3)
	v_mfma_f32_32x32x16_bf16 v[64:79], v[64:67], v[142:145], 0
	v_exp_f32_e32 v236, v96
	v_add_f32_e32 v96, 0, v184
	v_add_f32_e32 v96, v185, v96
	v_add_f32_e32 v96, v186, v96
	s_waitcnt lgkmcnt(2)
	v_mfma_f32_32x32x16_bf16 v[80:95], v[80:83], v[142:145], 0
	v_add_f32_e32 v96, v187, v96
	v_add_f32_e32 v96, v188, v96
	v_add_f32_e32 v96, v189, v96
	s_waitcnt lgkmcnt(1)
	v_mfma_f32_32x32x16_bf16 v[64:79], v[162:165], v[138:141], v[64:79]
	v_add_f32_e32 v96, v196, v96
	v_add_f32_e32 v96, v197, v96
	v_add_f32_e32 v96, v198, v96
	s_waitcnt lgkmcnt(0)
	v_mfma_f32_32x32x16_bf16 v[80:95], v[166:169], v[138:141], v[80:95]
	ds_read_b128 v[162:165], v209 offset:32768
	ds_read_b128 v[166:169], v209 offset:40960
	v_add_f32_e32 v96, v199, v96
	v_add_f32_e32 v96, v215, v96
	v_add_f32_e32 v96, v216, v96
	v_add_f32_e32 v96, v217, v96
	v_exp_f32_e32 v237, v97
	s_waitcnt lgkmcnt(1)
	v_mfma_f32_32x32x16_bf16 v[64:79], v[162:165], v[112:115], v[64:79]
	v_add_f32_e32 v96, v218, v96
	v_exp_f32_e32 v238, v98
	v_add_f32_e32 v96, v219, v96
	v_exp_f32_e32 v239, v99
	s_waitcnt lgkmcnt(0)
	v_mfma_f32_32x32x16_bf16 v[80:95], v[166:169], v[112:115], v[80:95]
	ds_read_b128 v[162:165], v210 offset:32768
	ds_read_b128 v[166:169], v210 offset:40960
	v_add_f32_e32 v96, v220, v96
	v_exp_f32_e32 v247, v100
	v_add_f32_e32 v96, v236, v96
	v_exp_f32_e32 v248, v101
	s_waitcnt lgkmcnt(1)
	v_mfma_f32_32x32x16_bf16 v[64:79], v[162:165], v[116:119], v[64:79]
	v_add_f32_e32 v96, v237, v96
	v_exp_f32_e32 v249, v102
	v_add_f32_e32 v96, v238, v96
	v_exp_f32_e32 v252, v103
	s_waitcnt lgkmcnt(0)
	v_mfma_f32_32x32x16_bf16 v[80:95], v[166:169], v[116:119], v[80:95]
	ds_read_b128 v[162:165], v190 offset:32768
	ds_read_b128 v[166:169], v190 offset:40960
	v_add_f32_e32 v96, v239, v96
	v_add_f32_e32 v96, v247, v96
	v_add_f32_e32 v96, v248, v96
	v_add_f32_e32 v96, v249, v96
	v_add_f32_e32 v96, v252, v96
	v_add_f32_e32 v96, v170, v96
	s_waitcnt lgkmcnt(1)
	v_mfma_f32_32x32x16_bf16 v[64:79], v[162:165], v[120:123], v[64:79]
	v_add_f32_e32 v96, v171, v96
	v_add_f32_e32 v96, v172, v96
	v_add_f32_e32 v96, v173, v96
	v_add_f32_e32 v96, v174, v96
	v_add_f32_e32 v96, v175, v96
	s_waitcnt lgkmcnt(0)
	v_mfma_f32_32x32x16_bf16 v[80:95], v[166:169], v[120:123], v[80:95]
	ds_read_b128 v[162:165], v191 offset:32768
	ds_read_b128 v[166:169], v191 offset:40960
	v_add_f32_e32 v96, v176, v96
	v_add_f32_e32 v181, v111, v96
	v_mov_b32_e32 v183, v181
	s_nop 1
	v_permlane32_swap_b32_e32 v181, v183
	v_pk_add_f32 v[96:97], v[180:181], v[182:183]
	s_waitcnt lgkmcnt(1)
	v_mfma_f32_32x32x16_bf16 v[64:79], v[162:165], v[124:127], v[64:79]
	s_nop 0
	v_add_f32_e32 v96, v128, v96
	v_add_f32_e32 v128, v96, v97
	v_cvt_pk_bf16_f32 v96, v184, v185
	v_cvt_pk_bf16_f32 v97, v186, v187
	s_waitcnt lgkmcnt(0)
	v_mfma_f32_32x32x16_bf16 v[80:95], v[166:169], v[124:127], v[80:95]
	ds_read_b128 v[162:165], v192 offset:32768
	ds_read_b128 v[166:169], v192 offset:40960
	v_cvt_pk_bf16_f32 v98, v188, v189
	v_cvt_pk_bf16_f32 v99, v196, v197
	v_cvt_pk_bf16_f32 v100, v198, v199
	v_cvt_pk_bf16_f32 v101, v215, v216
	v_cvt_pk_bf16_f32 v102, v217, v218
	v_cvt_pk_bf16_f32 v103, v219, v220
	s_waitcnt lgkmcnt(1)
	v_mfma_f32_32x32x16_bf16 v[64:79], v[162:165], v[130:133], v[64:79]
	v_cvt_pk_bf16_f32 v104, v236, v237
	v_cvt_pk_bf16_f32 v105, v238, v239
	v_cvt_pk_bf16_f32 v106, v247, v248
	v_cvt_pk_bf16_f32 v107, v249, v252
	v_cvt_pk_bf16_f32 v108, v170, v171
	s_waitcnt lgkmcnt(0)
	v_mfma_f32_32x32x16_bf16 v[80:95], v[166:169], v[130:133], v[80:95]
	ds_read_b128 v[162:165], v193 offset:32768
	ds_read_b128 v[166:169], v193 offset:40960
	ds_read_b64_tr_b16 v[180:181], v206 offset:0x4000
	ds_read_b64_tr_b16 v[182:183], v206 offset:0x4800
	ds_read_b64_tr_b16 v[184:185], v206 offset:0x5000
	ds_read_b64_tr_b16 v[186:187], v206 offset:0x5800
	ds_read_b64_tr_b16 v[216:217], v206 offset:0x6000
	ds_read_b64_tr_b16 v[218:219], v206 offset:0x6800
	ds_read_b64_tr_b16 v[220:221], v206 offset:0x7000
	ds_read_b64_tr_b16 v[222:223], v206 offset:0x7800
	v_cvt_pk_bf16_f32 v109, v172, v173
	v_cvt_pk_bf16_f32 v110, v174, v175
	v_cvt_pk_bf16_f32 v111, v176, v111
	s_nop 0
	v_permlane32_swap_b32_e32 v96, v98
	v_permlane32_swap_b32_e32 v97, v99
	s_waitcnt lgkmcnt(9)
	v_mfma_f32_32x32x16_bf16 v[64:79], v[162:165], v[134:137], v[64:79]
	v_permlane32_swap_b32_e32 v100, v102
	v_permlane32_swap_b32_e32 v101, v103
	v_permlane32_swap_b32_e32 v104, v106
	v_permlane32_swap_b32_e32 v105, v107
	v_permlane32_swap_b32_e32 v108, v110
	s_waitcnt lgkmcnt(8)
	v_mfma_f32_32x32x16_bf16 v[80:95], v[166:169], v[134:137], v[80:95]
	v_permlane32_swap_b32_e32 v109, v111
	s_waitcnt vmcnt(0)
	ds_write_b128 v211, v[146:149]
	s_waitcnt lgkmcnt(7)
	v_mfma_f32_32x32x16_bf16 v[0:15], v[96:99], v[180:183], v[0:15]
	ds_read_b64_tr_b16 v[180:181], v206 offset:0x4200
	ds_read_b64_tr_b16 v[182:183], v206 offset:0x4a00
	v_add_co_u32_e32 v166, vcc, s52, v178
	s_nop 1
	v_addc_co_u32_e32 v167, vcc, -1, v179, vcc
	v_add_co_u32_e32 v170, vcc, s53, v178
	s_nop 1
	v_addc_co_u32_e32 v171, vcc, -1, v179, vcc
	s_waitcnt lgkmcnt(7)
; #define SLOAD(i, k0) do { sr_[i].vs0 = ld8(&Vh[(long)((k0) + sr) * LDK + sc]); sr_[i].vs1 = ld8(&Vh[(long)((k0) + 32 + sr) * LDK + sc]); \
;     sr_[i].ks0 = ld8(&Kh[(long)((k0) + sr) * LDK + sc]); sr_[i].ks1 = ld8(&Kh[(long)((k0) + 32 + sr) * LDK + sc]); } while (0)
; #define SWAIT() asm volatile("s_waitcnt vmcnt(4)" ::: "memory")
; #define SWRITE_I(B, i) do { LDSV(wv0 + (B) * 16384) = sr_[i].vs0; LDSV(wv1 + (B) * 16384) = sr_[i].vs1; LDSV(wk0 + (B) * 16384) = sr_[i].ks0; LDSV(wk1 + (B) * 16384) = sr_[i].ks1; } while (0)
; #define NOP_() do { } while (0)
; template <int BOFF> __device__ __forceinline__ void qkt_i(f32x16& p0, f32x16& p1, const int (&kb)[4], const bf16x8* qr) {
;   p0 = f32x16{}; p1 = f32x16{};
; #pragma unroll
;   for (int d0 = 0; d0 < 8; ++d0) { const int off = BOFF + (d0 >> 2) * 128;
;     const bf16x8 b0 = LDSV(kb[d0 & 3] + off), b1 = LDSV(kb[d0 & 3] + off + 8192);
;     p0 = __builtin_amdgcn_mfma_f32_32x32x16_bf16(b0, qr[d0], p0, 0, 0, 0);
;     p1 = __builtin_amdgcn_mfma_f32_32x32x16_bf16(b1, qr[d0], p1, 0, 0, 0); }
; }
; template <bool PARTIAL, bool FIXED> ...
;     ...
;   int j = 1;
;   for (; j + 6 < NT; j += 6) {
;     HALF_B(1, 0, SLOAD(1, (j + 2) * KVBLK), do { SWAIT(); SWRITE_I(2, 0); } while (0));
;     HALF_A(2, 1, NOP_(), SLOAD(0, (j + 3) * KVBLK), do { SWAIT(); SWRITE_I(0, 1); } while (0));
;     HALF_B(0, 2, SLOAD(1, (j + 4) * KVBLK), do { SWAIT(); SWRITE_I(1, 0); } while (0));
;     HALF_A(1, 0, NOP_(), SLOAD(0, (j + 5) * KVBLK), do { SWAIT(); SWRITE_I(2, 1); } while (0));
;     HALF_B(2, 1, SLOAD(1, (j + 6) * KVBLK), do { SWAIT(); SWRITE_I(0, 0); } while (0));
;     HALF_A(0, 2, NOP_(), SLOAD(0, (j + 7) * KVBLK), do { SWAIT(); SWRITE_I(1, 1); } while (0));
	v_mfma_f32_32x32x16_bf16 v[0:15], v[100:103], v[184:187], v[0:15]
	ds_read_b64_tr_b16 v[184:185], v206 offset:0x5200
	ds_read_b64_tr_b16 v[186:187], v206 offset:0x5a00
	global_load_dwordx4 v[162:165], v[166:167], off
	global_load_dwordx4 v[166:169], v[166:167], off offset:-512
	global_load_dwordx4 v[174:177], v[170:171], off
	global_load_dwordx4 v[170:173], v[170:171], off offset:-512
	s_waitcnt lgkmcnt(7)
	v_mfma_f32_32x32x16_bf16 v[0:15], v[104:107], v[216:219], v[0:15]
	ds_read_b64_tr_b16 v[216:217], v206 offset:0x6200
	ds_read_b64_tr_b16 v[218:219], v206 offset:0x6a00
	s_waitcnt lgkmcnt(7)
	v_mfma_f32_32x32x16_bf16 v[0:15], v[108:111], v[220:223], v[0:15]
	ds_read_b64_tr_b16 v[220:221], v206 offset:0x7200
	ds_read_b64_tr_b16 v[222:223], v206 offset:0x7a00
	ds_write_b128 v212, v[158:161]
	s_waitcnt lgkmcnt(7)
	v_mfma_f32_32x32x16_bf16 v[16:31], v[96:99], v[180:183], v[16:31]
	ds_read_b64_tr_b16 v[180:181], v206 offset:0x4400
	ds_read_b64_tr_b16 v[182:183], v206 offset:0x4c00
	s_waitcnt lgkmcnt(7)
	v_mfma_f32_32x32x16_bf16 v[16:31], v[100:103], v[184:187], v[16:31]
	ds_read_b64_tr_b16 v[184:185], v206 offset:0x5400
	ds_read_b64_tr_b16 v[186:187], v206 offset:0x5c00
	s_waitcnt lgkmcnt(7)
	v_mfma_f32_32x32x16_bf16 v[16:31], v[104:107], v[216:219], v[16:31]
	ds_read_b64_tr_b16 v[216:217], v206 offset:0x6400
	ds_read_b64_tr_b16 v[218:219], v206 offset:0x6c00
	s_waitcnt lgkmcnt(7)
	v_mfma_f32_32x32x16_bf16 v[16:31], v[108:111], v[220:223], v[16:31]
	ds_read_b64_tr_b16 v[220:221], v206 offset:0x7400
	ds_read_b64_tr_b16 v[222:223], v206 offset:0x7c00
	ds_write_b128 v213, v[150:153]
	s_waitcnt lgkmcnt(7)
	v_mfma_f32_32x32x16_bf16 v[32:47], v[96:99], v[180:183], v[32:47]
	ds_read_b64_tr_b16 v[180:181], v206 offset:0x4600
	ds_read_b64_tr_b16 v[182:183], v206 offset:0x4e00
	v_exp_f32_e32 v188, v72
	v_exp_f32_e32 v189, v73
	s_waitcnt lgkmcnt(7)
	v_mfma_f32_32x32x16_bf16 v[32:47], v[100:103], v[184:187], v[32:47]
	ds_read_b64_tr_b16 v[184:185], v206 offset:0x5600
	ds_read_b64_tr_b16 v[186:187], v206 offset:0x5e00
	v_exp_f32_e32 v196, v74
	v_exp_f32_e32 v197, v75
	s_waitcnt lgkmcnt(7)
	v_mfma_f32_32x32x16_bf16 v[32:47], v[104:107], v[216:219], v[32:47]
	ds_read_b64_tr_b16 v[216:217], v206 offset:0x6600
	ds_read_b64_tr_b16 v[218:219], v206 offset:0x6e00
	v_exp_f32_e32 v198, v76
	v_exp_f32_e32 v199, v77
	s_waitcnt lgkmcnt(7)
	v_mfma_f32_32x32x16_bf16 v[32:47], v[108:111], v[220:223], v[32:47]
	ds_read_b64_tr_b16 v[220:221], v206 offset:0x7600
	ds_read_b64_tr_b16 v[222:223], v206 offset:0x7e00
	ds_write_b128 v214, v[154:157]
	s_waitcnt lgkmcnt(7)
	v_mfma_f32_32x32x16_bf16 v[48:63], v[96:99], v[180:183], v[48:63]
	v_exp_f32_e32 v180, v64
	v_exp_f32_e32 v181, v65
	v_exp_f32_e32 v182, v66
	v_exp_f32_e32 v183, v67
	s_waitcnt lgkmcnt(5)
	v_mfma_f32_32x32x16_bf16 v[48:63], v[100:103], v[184:187], v[48:63]
	v_exp_f32_e32 v184, v68
	v_exp_f32_e32 v185, v69
	v_exp_f32_e32 v186, v70
	v_exp_f32_e32 v187, v71
	s_waitcnt lgkmcnt(3)
	v_mfma_f32_32x32x16_bf16 v[48:63], v[104:107], v[216:219], v[48:63]
	v_exp_f32_e32 v216, v78
	v_exp_f32_e32 v217, v79
	s_waitcnt lgkmcnt(0)
	s_barrier
	v_mfma_f32_32x32x16_bf16 v[48:63], v[108:111], v[220:223], v[48:63]
	ds_read_b128 v[64:67], v207
	ds_read_b128 v[68:71], v207 offset:8192
	ds_read_b128 v[146:149], v208
	ds_read_b128 v[150:153], v208 offset:8192
	v_exp_f32_e32 v154, v88
	v_exp_f32_e32 v155, v89
	v_exp_f32_e32 v156, v90
	v_exp_f32_e32 v157, v91
	v_exp_f32_e32 v158, v92
	v_exp_f32_e32 v159, v93
	v_exp_f32_e32 v160, v94
	v_exp_f32_e32 v95, v95
	s_waitcnt lgkmcnt(3)
	v_mfma_f32_32x32x16_bf16 v[96:111], v[64:67], v[142:145], 0
	v_exp_f32_e32 v236, v80
	v_add_f32_e32 v80, 0, v180
	v_add_f32_e32 v80, v181, v80
	v_add_f32_e32 v80, v182, v80
	s_waitcnt lgkmcnt(2)
	v_mfma_f32_32x32x16_bf16 v[64:79], v[68:71], v[142:145], 0
	v_add_f32_e32 v80, v183, v80
	v_add_f32_e32 v80, v184, v80
	v_add_f32_e32 v80, v185, v80
	s_waitcnt lgkmcnt(1)
	v_mfma_f32_32x32x16_bf16 v[96:111], v[146:149], v[138:141], v[96:111]
	v_add_f32_e32 v80, v186, v80
	v_add_f32_e32 v80, v187, v80
	v_add_f32_e32 v80, v188, v80
	s_waitcnt lgkmcnt(0)
	v_mfma_f32_32x32x16_bf16 v[64:79], v[150:153], v[138:141], v[64:79]
	ds_read_b128 v[146:149], v209
	ds_read_b128 v[150:153], v209 offset:8192
	v_add_f32_e32 v80, v189, v80
	v_add_f32_e32 v80, v196, v80
	v_add_f32_e32 v80, v197, v80
	v_add_f32_e32 v80, v198, v80
	v_exp_f32_e32 v237, v81
	s_waitcnt lgkmcnt(1)
	v_mfma_f32_32x32x16_bf16 v[96:111], v[146:149], v[112:115], v[96:111]
	v_add_f32_e32 v80, v199, v80
	v_exp_f32_e32 v238, v82
	v_add_f32_e32 v80, v216, v80
	v_exp_f32_e32 v239, v83
	s_waitcnt lgkmcnt(0)
	v_mfma_f32_32x32x16_bf16 v[64:79], v[150:153], v[112:115], v[64:79]
	ds_read_b128 v[146:149], v210
	ds_read_b128 v[150:153], v210 offset:8192
	v_add_f32_e32 v80, v217, v80
	v_exp_f32_e32 v247, v84
	v_add_f32_e32 v80, v236, v80
	v_exp_f32_e32 v248, v85
	s_waitcnt lgkmcnt(1)
	v_mfma_f32_32x32x16_bf16 v[96:111], v[146:149], v[116:119], v[96:111]
	v_add_f32_e32 v80, v237, v80
	v_exp_f32_e32 v249, v86
	v_add_f32_e32 v80, v238, v80
	v_exp_f32_e32 v252, v87
	s_waitcnt lgkmcnt(0)
	v_mfma_f32_32x32x16_bf16 v[64:79], v[150:153], v[116:119], v[64:79]
	ds_read_b128 v[146:149], v190 offset:0
	ds_read_b128 v[150:153], v190 offset:8192
	v_add_f32_e32 v80, v239, v80
	v_add_f32_e32 v80, v247, v80
	v_add_f32_e32 v80, v248, v80
	v_add_f32_e32 v80, v249, v80
	v_add_f32_e32 v80, v252, v80
	v_add_f32_e32 v80, v154, v80
	s_waitcnt lgkmcnt(1)
	v_mfma_f32_32x32x16_bf16 v[96:111], v[146:149], v[120:123], v[96:111]
	v_add_f32_e32 v80, v155, v80
	v_add_f32_e32 v80, v156, v80
	v_add_f32_e32 v80, v157, v80
	v_add_f32_e32 v80, v158, v80
	v_add_f32_e32 v80, v159, v80
	s_waitcnt lgkmcnt(0)
; #define SLOAD(i, k0) do { sr_[i].vs0 = ld8(&Vh[(long)((k0) + sr) * LDK + sc]); sr_[i].vs1 = ld8(&Vh[(long)((k0) + 32 + sr) * LDK + sc]); \
;     sr_[i].ks0 = ld8(&Kh[(long)((k0) + sr) * LDK + sc]); sr_[i].ks1 = ld8(&Kh[(long)((k0) + 32 + sr) * LDK + sc]); } while (0)
; #define SWAIT() asm volatile("s_waitcnt vmcnt(4)" ::: "memory")
; #define SWRITE_I(B, i) do { LDSV(wv0 + (B) * 16384) = sr_[i].vs0; LDSV(wv1 + (B) * 16384) = sr_[i].vs1; LDSV(wk0 + (B) * 16384) = sr_[i].ks0; LDSV(wk1 + (B) * 16384) = sr_[i].ks1; } while (0)
; #define NOP_() do { } while (0)
; __device__ __forceinline__ void finishSM(f32x16& p0, f32x16& p1, float alpha, float& l_reg, bf16x8& pa0, bf16x8& pa1, bf16x8& pa2, bf16x8& pa3) {
;   for (int r = 0; r < 16; ++r) p1[r] = __builtin_amdgcn_exp2f(p1[r]);
;   float ps = 0; for (int r = 0; r < 16; ++r) ps += p0[r]; for (int r = 0; r < 16; ++r) ps += p1[r];
;   { auto rr = __builtin_amdgcn_permlane32_swap(__float_as_uint(ps), __float_as_uint(ps), false, false);
;     ps = __uint_as_float(rr[0]) + __uint_as_float(rr[1]); }
;   l_reg = l_reg * alpha + ps;
;     ...
;   PK4(p0, 0, pa0); PK4(p0, 8, pa1); PK4(p1, 0, pa2); PK4(p1, 8, pa3);
;     ...
; }
; template <bool PARTIAL, bool FIXED> ...
;     ...
;   int j = 1;
;   for (; j + 6 < NT; j += 6) {
;     HALF_B(1, 0, SLOAD(1, (j + 2) * KVBLK), do { SWAIT(); SWRITE_I(2, 0); } while (0));
;     HALF_A(2, 1, NOP_(), SLOAD(0, (j + 3) * KVBLK), do { SWAIT(); SWRITE_I(0, 1); } while (0));
;     HALF_B(0, 2, SLOAD(1, (j + 4) * KVBLK), do { SWAIT(); SWRITE_I(1, 0); } while (0));
;     HALF_A(1, 0, NOP_(), SLOAD(0, (j + 5) * KVBLK), do { SWAIT(); SWRITE_I(2, 1); } while (0));
;     HALF_B(2, 1, SLOAD(1, (j + 6) * KVBLK), do { SWAIT(); SWRITE_I(0, 0); } while (0));
;     HALF_A(0, 2, NOP_(), SLOAD(0, (j + 7) * KVBLK), do { SWAIT(); SWRITE_I(1, 1); } while (0));
	v_mfma_f32_32x32x16_bf16 v[64:79], v[150:153], v[120:123], v[64:79]
	ds_read_b128 v[146:149], v191 offset:0
	ds_read_b128 v[150:153], v191 offset:8192
	v_add_f32_e32 v80, v160, v80
	v_add_f32_e32 v80, v95, v80
	v_mov_b32_e32 v81, v80
	s_nop 1
	v_permlane32_swap_b32_e32 v80, v81
	v_add_f32_e32 v80, v80, v81
	s_waitcnt lgkmcnt(1)
	v_mfma_f32_32x32x16_bf16 v[96:111], v[146:149], v[124:127], v[96:111]
	v_add_f32_e32 v215, v128, v80
	v_cvt_pk_bf16_f32 v80, v180, v181
	v_cvt_pk_bf16_f32 v81, v182, v183
	v_cvt_pk_bf16_f32 v82, v184, v185
	v_cvt_pk_bf16_f32 v83, v186, v187
	s_waitcnt lgkmcnt(0)
	v_mfma_f32_32x32x16_bf16 v[64:79], v[150:153], v[124:127], v[64:79]
	ds_read_b128 v[146:149], v192 offset:0
	ds_read_b128 v[150:153], v192 offset:8192
	v_cvt_pk_bf16_f32 v84, v188, v189
	v_cvt_pk_bf16_f32 v85, v196, v197
	v_cvt_pk_bf16_f32 v86, v198, v199
	v_cvt_pk_bf16_f32 v87, v216, v217
	v_cvt_pk_bf16_f32 v88, v236, v237
	v_cvt_pk_bf16_f32 v89, v238, v239
	s_waitcnt lgkmcnt(1)
	v_mfma_f32_32x32x16_bf16 v[96:111], v[146:149], v[130:133], v[96:111]
	v_cvt_pk_bf16_f32 v90, v247, v248
	v_cvt_pk_bf16_f32 v91, v249, v252
	v_cvt_pk_bf16_f32 v92, v154, v155
	v_cvt_pk_bf16_f32 v93, v156, v157
	v_cvt_pk_bf16_f32 v94, v158, v159
	s_waitcnt lgkmcnt(0)
	v_mfma_f32_32x32x16_bf16 v[64:79], v[150:153], v[130:133], v[64:79]
	ds_read_b128 v[146:149], v193 offset:0
	ds_read_b128 v[150:153], v193 offset:8192
	ds_read_b64_tr_b16 v[180:181], v206 offset:0x8000
	ds_read_b64_tr_b16 v[182:183], v206 offset:0x8800
	ds_read_b64_tr_b16 v[184:185], v206 offset:0x9000
	ds_read_b64_tr_b16 v[186:187], v206 offset:0x9800
	ds_read_b64_tr_b16 v[216:217], v206 offset:0xa000
	ds_read_b64_tr_b16 v[218:219], v206 offset:0xa800
	ds_read_b64_tr_b16 v[220:221], v206 offset:0xb000
	ds_read_b64_tr_b16 v[222:223], v206 offset:0xb800
	v_cvt_pk_bf16_f32 v95, v160, v95
	s_nop 0
	v_permlane32_swap_b32_e32 v80, v82
	v_permlane32_swap_b32_e32 v81, v83
	v_permlane32_swap_b32_e32 v84, v86
	v_permlane32_swap_b32_e32 v85, v87
	s_waitcnt lgkmcnt(9)
	v_mfma_f32_32x32x16_bf16 v[96:111], v[146:149], v[134:137], v[96:111]
	v_permlane32_swap_b32_e32 v88, v90
	v_permlane32_swap_b32_e32 v89, v91
	v_permlane32_swap_b32_e32 v92, v94
	v_permlane32_swap_b32_e32 v93, v95
	s_waitcnt lgkmcnt(8)
	v_mfma_f32_32x32x16_bf16 v[64:79], v[150:153], v[134:137], v[64:79]
	s_waitcnt vmcnt(0)
	ds_write_b128 v211, v[162:165] offset:16384
	s_waitcnt lgkmcnt(7)
	v_mfma_f32_32x32x16_bf16 v[0:15], v[80:83], v[180:183], v[0:15]
	ds_read_b64_tr_b16 v[180:181], v206 offset:0x8200
	ds_read_b64_tr_b16 v[182:183], v206 offset:0x8a00
	v_add_co_u32_e32 v150, vcc, s58, v178
	s_nop 1
	v_addc_co_u32_e32 v151, vcc, -1, v179, vcc
	s_waitcnt lgkmcnt(7)
	v_mfma_f32_32x32x16_bf16 v[0:15], v[84:87], v[184:187], v[0:15]
	ds_read_b64_tr_b16 v[184:185], v206 offset:0x9200
	ds_read_b64_tr_b16 v[186:187], v206 offset:0x9a00
	global_load_dwordx4 v[146:149], v[150:151], off
	global_load_dwordx4 v[154:157], v[150:151], off offset:-512
	global_load_dwordx4 v[150:153], v[178:179], off
	global_load_dwordx4 v[158:161], v[178:179], off offset:-512
	s_waitcnt lgkmcnt(7)
	v_mfma_f32_32x32x16_bf16 v[0:15], v[88:91], v[216:219], v[0:15]
	ds_read_b64_tr_b16 v[216:217], v206 offset:0xa200
	ds_read_b64_tr_b16 v[218:219], v206 offset:0xaa00
	s_waitcnt lgkmcnt(7)
	v_mfma_f32_32x32x16_bf16 v[0:15], v[92:95], v[220:223], v[0:15]
	ds_read_b64_tr_b16 v[220:221], v206 offset:0xb200
	ds_read_b64_tr_b16 v[222:223], v206 offset:0xba00
	ds_write_b128 v212, v[174:177] offset:16384
	s_waitcnt lgkmcnt(7)
	v_mfma_f32_32x32x16_bf16 v[16:31], v[80:83], v[180:183], v[16:31]
	ds_read_b64_tr_b16 v[180:181], v206 offset:0x8400
	ds_read_b64_tr_b16 v[182:183], v206 offset:0x8c00
	s_waitcnt lgkmcnt(7)
	v_mfma_f32_32x32x16_bf16 v[16:31], v[84:87], v[184:187], v[16:31]
	ds_read_b64_tr_b16 v[184:185], v206 offset:0x9400
	ds_read_b64_tr_b16 v[186:187], v206 offset:0x9c00
	s_waitcnt lgkmcnt(7)
	v_mfma_f32_32x32x16_bf16 v[16:31], v[88:91], v[216:219], v[16:31]
	ds_read_b64_tr_b16 v[216:217], v206 offset:0xa400
	ds_read_b64_tr_b16 v[218:219], v206 offset:0xac00
	s_waitcnt lgkmcnt(7)
	v_mfma_f32_32x32x16_bf16 v[16:31], v[92:95], v[220:223], v[16:31]
	ds_read_b64_tr_b16 v[220:221], v206 offset:0xb400
	ds_read_b64_tr_b16 v[222:223], v206 offset:0xbc00
	ds_write_b128 v213, v[166:169] offset:16384
	s_waitcnt lgkmcnt(7)
	v_mfma_f32_32x32x16_bf16 v[32:47], v[80:83], v[180:183], v[32:47]
	ds_read_b64_tr_b16 v[180:181], v206 offset:0x8600
	ds_read_b64_tr_b16 v[182:183], v206 offset:0x8e00
	v_exp_f32_e32 v229, v96
	v_exp_f32_e32 v243, v97
	s_waitcnt lgkmcnt(7)
	v_mfma_f32_32x32x16_bf16 v[32:47], v[84:87], v[184:187], v[32:47]
	ds_read_b64_tr_b16 v[184:185], v206 offset:0x9600
	ds_read_b64_tr_b16 v[186:187], v206 offset:0x9e00
	v_exp_f32_e32 v244, v98
	v_exp_f32_e32 v246, v99
	s_waitcnt lgkmcnt(7)
	v_mfma_f32_32x32x16_bf16 v[32:47], v[88:91], v[216:219], v[32:47]
	ds_read_b64_tr_b16 v[216:217], v206 offset:0xa600
	ds_read_b64_tr_b16 v[218:219], v206 offset:0xae00
	v_exp_f32_e32 v242, v100
	v_exp_f32_e32 v245, v101
	s_waitcnt lgkmcnt(7)
	v_mfma_f32_32x32x16_bf16 v[32:47], v[92:95], v[220:223], v[32:47]
	ds_read_b64_tr_b16 v[220:221], v206 offset:0xb600
	ds_read_b64_tr_b16 v[222:223], v206 offset:0xbe00
	v_exp_f32_e32 v227, v102
	v_exp_f32_e32 v228, v103
	ds_write_b128 v214, v[170:173] offset:16384
	s_waitcnt lgkmcnt(7)
	v_mfma_f32_32x32x16_bf16 v[48:63], v[80:83], v[180:183], v[48:63]
	s_waitcnt lgkmcnt(5)
	v_mfma_f32_32x32x16_bf16 v[48:63], v[84:87], v[184:187], v[48:63]
	v_exp_f32_e32 v226, v105
	v_exp_f32_e32 v224, v106
	v_exp_f32_e32 v225, v107
	s_add_i32 s28, s28, 6
	v_lshl_add_u64 v[178:179], v[178:179], 0, s[60:61]
	s_waitcnt lgkmcnt(3)
	v_mfma_f32_32x32x16_bf16 v[48:63], v[88:91], v[216:219], v[48:63]
	v_exp_f32_e32 v219, v110
	s_cmpk_lt_u32 s28, 0x75
	s_waitcnt lgkmcnt(1)
	v_mfma_f32_32x32x16_bf16 v[48:63], v[92:95], v[220:223], v[48:63]
	v_exp_f32_e32 v223, v104
	v_exp_f32_e32 v220, v108
	v_exp_f32_e32 v222, v109
	v_exp_f32_e32 v221, v111
	s_cbranch_scc1 .LBB0_352
; #define SWRITE_I(B, i) do { LDSV(wv0 + (B) * 16384) = sr_[i].vs0; LDSV(wv1 + (B) * 16384) = sr_[i].vs1; LDSV(wk0 + (B) * 16384) = sr_[i].ks0; LDSV(wk1 + (B) * 16384) = sr_[i].ks1; } while (0)
; #define NOP_() do { } while (0)
; __device__ __forceinline__ void finishSM(f32x16& p0, f32x16& p1, float alpha, float& l_reg, bf16x8& pa0, bf16x8& pa1, bf16x8& pa2, bf16x8& pa3) {
;   for (int r = 0; r < 16; ++r) p1[r] = __builtin_amdgcn_exp2f(p1[r]);
;   float ps = 0; for (int r = 0; r < 16; ++r) ps += p0[r]; for (int r = 0; r < 16; ++r) ps += p1[r];
;   { auto rr = __builtin_amdgcn_permlane32_swap(__float_as_uint(ps), __float_as_uint(ps), false, false);
;     ps = __uint_as_float(rr[0]) + __uint_as_float(rr[1]); }
;   l_reg = l_reg * alpha + ps;
;     ...
;   PK4(p0, 0, pa0); PK4(p0, 8, pa1); PK4(p1, 0, pa2); PK4(p1, 8, pa3);
;     ...
; }
; template <bool PARTIAL, bool FIXED> ...
;     ...
;   if constexpr (!PARTIAL) { const int i1 = tid & 255;
;     warm0 = *(const unsigned*)(Qb_n + (long)(tid >> 1) * LDQ + (tid & 1) * 64);
;     warm1 = *(const unsigned*)((tid < 256 ? Kh_n : Vh_n) + (long)(i1 >> 1) * LDK + (i1 & 1) * 64); }
;   HALF_B(1, 0, NOP_(), SWRITE_I(2, 0));
	v_mov_b32_e32 v252, 0x7fc00000
	v_readlane_b32 s8, v255, 42
	v_readlane_b32 s9, v255, 43
	s_add_u32 s2, s8, s6
	s_addc_u32 s3, s9, s7
	s_lshl_b32 s4, s65, 1
	s_add_u32 s2, s2, s4
	s_addc_u32 s3, s3, 0
	v_ashrrev_i32_e32 v82, 1, v195
	v_mov_b64_e32 v[80:81], s[2:3]
	v_mad_i64_i32 v[80:81], s[2:3], v82, s17, v[80:81]
	v_lshlrev_b32_e32 v82, 7, v195
	v_and_b32_e32 v128, 0x80, v82
	v_lshl_add_u64 v[80:81], v[80:81], 0, v[128:129]
	s_add_u32 s4, s8, s64
	global_load_dword v216, v[80:81], off
	v_cmp_gt_i32_e32 vcc, s14, v195
	v_mov_b32_e32 v80, 0xa00
	v_mov_b32_e32 v81, 0x800
	s_addc_u32 s5, s9, s57
	v_cndmask_b32_e32 v80, v80, v81, vcc
	v_mov_b32_e32 v81, v129
	v_bfe_u32 v82, v195, 1, 7
	v_lshl_add_u64 v[80:81], s[4:5], 0, v[80:81]
	s_lshl_b32 s46, s56, 1
	v_mul_u32_u24_e32 v82, 0x600, v82
	v_lshl_add_u64 v[80:81], v[80:81], 0, s[46:47]
	v_lshlrev_b32_e32 v82, 1, v82
	v_mov_b32_e32 v83, v129
	v_lshl_add_u64 v[80:81], v[80:81], 0, v[82:83]
	v_lshl_add_u64 v[80:81], v[80:81], 0, v[128:129]
	global_load_dword v217, v[80:81], off
	v_and_b32_e32 v247, 0x3fffffc0, v195
	s_waitcnt lgkmcnt(0)
	s_barrier
	ds_read_b128 v[80:83], v207 offset:16384
	ds_read_b128 v[96:99], v207 offset:24576
	ds_read_b128 v[100:103], v208 offset:16384
	ds_read_b128 v[170:173], v208 offset:24576
	v_exp_f32_e32 v104, v68
	v_exp_f32_e32 v105, v69
	s_waitcnt lgkmcnt(3)
	v_mfma_f32_32x32x16_bf16 v[80:95], v[80:83], v[142:145], 0
	v_exp_f32_e32 v106, v70
	v_exp_f32_e32 v107, v71
	v_exp_f32_e32 v108, v72
	v_exp_f32_e32 v109, v73
	v_exp_f32_e32 v110, v74
	v_exp_f32_e32 v111, v75
	v_exp_f32_e32 v196, v76
	s_waitcnt lgkmcnt(1)
	v_mfma_f32_32x32x16_bf16 v[80:95], v[100:103], v[138:141], v[80:95]
	ds_read_b128 v[100:103], v209 offset:16384
	ds_read_b128 v[162:165], v209 offset:24576
	v_exp_f32_e32 v197, v77
	v_exp_f32_e32 v198, v78
	v_exp_f32_e32 v79, v79
	s_waitcnt lgkmcnt(1)
	v_mfma_f32_32x32x16_bf16 v[80:95], v[100:103], v[112:115], v[80:95]
	ds_read_b128 v[100:103], v210 offset:16384
	ds_read_b128 v[166:169], v210 offset:24576
	s_waitcnt lgkmcnt(1)
	v_mfma_f32_32x32x16_bf16 v[80:95], v[100:103], v[116:119], v[80:95]
	ds_read_b128 v[100:103], v190 offset:16384
	ds_read_b128 v[174:177], v190 offset:24576
	s_waitcnt lgkmcnt(1)
	v_mfma_f32_32x32x16_bf16 v[80:95], v[100:103], v[120:123], v[80:95]
	ds_read_b128 v[100:103], v191 offset:16384
	ds_read_b128 v[178:181], v191 offset:24576
	s_waitcnt lgkmcnt(1)
	v_mfma_f32_32x32x16_bf16 v[80:95], v[100:103], v[124:127], v[80:95]
	ds_read_b128 v[100:103], v192 offset:16384
	ds_read_b128 v[182:185], v192 offset:24576
	s_waitcnt lgkmcnt(1)
	v_mfma_f32_32x32x16_bf16 v[80:95], v[100:103], v[130:133], v[80:95]
	ds_read_b128 v[100:103], v193 offset:16384
	ds_read_b128 v[186:189], v193 offset:24576
	s_waitcnt lgkmcnt(1)
	v_mfma_f32_32x32x16_bf16 v[80:95], v[100:103], v[134:137], v[80:95]
	v_exp_f32_e32 v100, v64
	v_add_f32_e32 v64, 0, v229
	v_add_f32_e32 v64, v243, v64
	v_add_f32_e32 v64, v244, v64
	v_add_f32_e32 v64, v246, v64
	v_add_f32_e32 v64, v242, v64
	v_add_f32_e32 v64, v245, v64
	v_add_f32_e32 v64, v227, v64
	v_add_f32_e32 v64, v228, v64
	v_add_f32_e32 v64, v223, v64
	v_add_f32_e32 v64, v226, v64
	v_add_f32_e32 v64, v224, v64
	v_add_f32_e32 v64, v225, v64
	v_add_f32_e32 v64, v220, v64
	v_exp_f32_e32 v101, v65
	v_add_f32_e32 v64, v222, v64
	v_exp_f32_e32 v102, v66
	v_add_f32_e32 v64, v219, v64
	v_exp_f32_e32 v103, v67
	v_add_f32_e32 v64, v221, v64
	v_add_f32_e32 v64, v100, v64
	v_add_f32_e32 v64, v101, v64
	v_add_f32_e32 v64, v102, v64
	v_add_f32_e32 v64, v103, v64
	v_add_f32_e32 v64, v104, v64
	v_add_f32_e32 v64, v105, v64
	v_add_f32_e32 v64, v106, v64
	v_add_f32_e32 v64, v107, v64
	v_add_f32_e32 v64, v108, v64
	v_add_f32_e32 v64, v109, v64
	v_add_f32_e32 v64, v110, v64
	v_add_f32_e32 v64, v111, v64
	v_add_f32_e32 v64, v196, v64
	v_add_f32_e32 v64, v197, v64
	v_add_f32_e32 v64, v198, v64
	v_add_f32_e32 v128, v79, v64
	v_mov_b32_e32 v218, v128
	s_nop 1
	v_permlane32_swap_b32_e32 v128, v218
	v_cvt_pk_bf16_f32 v64, v229, v243
	v_cvt_pk_bf16_f32 v65, v244, v246
	v_cvt_pk_bf16_f32 v66, v242, v245
	v_cvt_pk_bf16_f32 v67, v227, v228
	v_cvt_pk_bf16_f32 v68, v223, v226
	v_cvt_pk_bf16_f32 v69, v224, v225
	v_cvt_pk_bf16_f32 v70, v220, v222
	v_cvt_pk_bf16_f32 v71, v219, v221
	v_cvt_pk_bf16_f32 v72, v100, v101
	v_cvt_pk_bf16_f32 v73, v102, v103
	v_cvt_pk_bf16_f32 v74, v104, v105
	v_cvt_pk_bf16_f32 v75, v106, v107
	v_cvt_pk_bf16_f32 v76, v108, v109
	v_cvt_pk_bf16_f32 v77, v110, v111
	v_cvt_pk_bf16_f32 v78, v196, v197
	v_cvt_pk_bf16_f32 v79, v198, v79
	s_nop 0
	v_permlane32_swap_b32_e32 v64, v66
	v_permlane32_swap_b32_e32 v65, v67
	v_permlane32_swap_b32_e32 v68, v70
	v_permlane32_swap_b32_e32 v69, v71
	v_permlane32_swap_b32_e32 v72, v74
	v_permlane32_swap_b32_e32 v73, v75
	v_permlane32_swap_b32_e32 v76, v78
	v_permlane32_swap_b32_e32 v77, v79
	ds_read_b64_tr_b16 v[100:101], v206 offset:0
	ds_read_b64_tr_b16 v[102:103], v206 offset:0x800
	ds_read_b64_tr_b16 v[104:105], v206 offset:0x1000
	ds_read_b64_tr_b16 v[106:107], v206 offset:0x1800
	ds_read_b64_tr_b16 v[108:109], v206 offset:0x2000
	ds_read_b64_tr_b16 v[110:111], v206 offset:0x2800
	ds_read_b64_tr_b16 v[220:221], v206 offset:0x3000
	ds_read_b64_tr_b16 v[222:223], v206 offset:0x3800
	s_waitcnt lgkmcnt(0)
	s_nop 0
	v_mfma_f32_32x32x16_bf16 v[0:15], v[64:67], v[100:103], v[0:15]
	ds_read_b64_tr_b16 v[100:101], v206 offset:0x200
	ds_read_b64_tr_b16 v[102:103], v206 offset:0xa00
	v_mfma_f32_32x32x16_bf16 v[0:15], v[68:71], v[104:107], v[0:15]
	ds_read_b64_tr_b16 v[104:105], v206 offset:0x1200
	ds_read_b64_tr_b16 v[106:107], v206 offset:0x1a00
	v_mfma_f32_32x32x16_bf16 v[0:15], v[72:75], v[108:111], v[0:15]
	ds_read_b64_tr_b16 v[108:109], v206 offset:0x2200
	ds_read_b64_tr_b16 v[110:111], v206 offset:0x2a00
	v_mfma_f32_32x32x16_bf16 v[0:15], v[76:79], v[220:223], v[0:15]
	ds_read_b64_tr_b16 v[220:221], v206 offset:0x3200
	ds_read_b64_tr_b16 v[222:223], v206 offset:0x3a00
	s_waitcnt lgkmcnt(0)
; #define SBAR() __builtin_amdgcn_sched_barrier(0)
; #define SWRITE_I(B, i) do { LDSV(wv0 + (B) * 16384) = sr_[i].vs0; LDSV(wv1 + (B) * 16384) = sr_[i].vs1; LDSV(wk0 + (B) * 16384) = sr_[i].ks0; LDSV(wk1 + (B) * 16384) = sr_[i].ks1; } while (0)
; #define NOP_() do { } while (0)
; template <int BOFF> __device__ __forceinline__ void qkt_i(f32x16& p0, f32x16& p1, const int (&kb)[4], const bf16x8* qr) {
;   p0 = f32x16{}; p1 = f32x16{};
; #pragma unroll
;   for (int d0 = 0; d0 < 8; ++d0) { const int off = BOFF + (d0 >> 2) * 128;
;     const bf16x8 b0 = LDSV(kb[d0 & 3] + off), b1 = LDSV(kb[d0 & 3] + off + 8192);
;     p0 = __builtin_amdgcn_mfma_f32_32x32x16_bf16(b0, qr[d0], p0, 0, 0, 0);
;     p1 = __builtin_amdgcn_mfma_f32_32x32x16_bf16(b1, qr[d0], p1, 0, 0, 0); }
; }
; template <int D0, int BOFF> __device__ __forceinline__ void pv_one_i(f32x16& od, int vb, bf16x8 pa0, bf16x8 pa1, bf16x8 pa2, bf16x8 pa3) {
;   const s16x4 l0 = tr_read<BOFF + v_rd_off(D0, 0, 0)>(vb), h0 = tr_read<BOFF + v_rd_off(D0, 0, 1)>(vb), l1 = tr_read<BOFF + v_rd_off(D0, 1, 0)>(vb), h1 = tr_read<BOFF + v_rd_off(D0, 1, 1)>(vb);
;   const s16x4 l2 = tr_read<BOFF + v_rd_off(D0, 2, 0)>(vb), h2 = tr_read<BOFF + v_rd_off(D0, 2, 1)>(vb), l3 = tr_read<BOFF + v_rd_off(D0, 3, 0)>(vb), h3 = tr_read<BOFF + v_rd_off(D0, 3, 1)>(vb);
;   asm volatile("s_waitcnt lgkmcnt(0)" ::: "memory"); SBAR();
;     ...
;   od = __builtin_amdgcn_mfma_f32_32x32x16_bf16(pa0, PK(l0, h0), od, 0, 0, 0);
;   od = __builtin_amdgcn_mfma_f32_32x32x16_bf16(pa1, PK(l1, h1), od, 0, 0, 0);
;   od = __builtin_amdgcn_mfma_f32_32x32x16_bf16(pa2, PK(l2, h2), od, 0, 0, 0);
;   od = __builtin_amdgcn_mfma_f32_32x32x16_bf16(pa3, PK(l3, h3), od, 0, 0, 0);
;     ...
; }
; template <int BOFF> __device__ __forceinline__ void pv_i(f32x16* o, int vb, bf16x8 pa0, bf16x8 pa1, bf16x8 pa2, bf16x8 pa3) {
;   pv_one_i<0, BOFF>(o[0], vb, pa0, pa1, pa2, pa3); pv_one_i<1, BOFF>(o[1], vb, pa0, pa1, pa2, pa3); pv_one_i<2, BOFF>(o[2], vb, pa0, pa1, pa2, pa3); pv_one_i<3, BOFF>(o[3], vb, pa0, pa1, pa2, pa3);
; template <bool PARTIAL, bool FIXED> ...
;     ...
;   HALF_B(1, 0, NOP_(), SWRITE_I(2, 0));
;   HALF_A(2, 1, do { if (mask_last) { asm volatile("; masked tail tile" ::: "memory"); const float NEG = -INFINITY; \
;       _Pragma("unroll") for (int r = 8; r < 16; ++r) pA0[r] = NEG; _Pragma("unroll") for (int r = 0; r < 16; ++r) pA1[r] = NEG; } } while (0), NOP_(), NOP_());
	v_mfma_f32_32x32x16_bf16 v[16:31], v[64:67], v[100:103], v[16:31]
	ds_read_b64_tr_b16 v[100:101], v206 offset:0x400
	ds_read_b64_tr_b16 v[102:103], v206 offset:0xc00
	v_mfma_f32_32x32x16_bf16 v[16:31], v[68:71], v[104:107], v[16:31]
	ds_read_b64_tr_b16 v[104:105], v206 offset:0x1400
	ds_read_b64_tr_b16 v[106:107], v206 offset:0x1c00
	v_mfma_f32_32x32x16_bf16 v[16:31], v[72:75], v[108:111], v[16:31]
	ds_read_b64_tr_b16 v[108:109], v206 offset:0x2400
	ds_read_b64_tr_b16 v[110:111], v206 offset:0x2c00
	v_mfma_f32_32x32x16_bf16 v[16:31], v[76:79], v[220:223], v[16:31]
	ds_read_b64_tr_b16 v[220:221], v206 offset:0x3400
	ds_read_b64_tr_b16 v[222:223], v206 offset:0x3c00
	s_waitcnt lgkmcnt(0)
	v_mfma_f32_32x32x16_bf16 v[32:47], v[64:67], v[100:103], v[32:47]
	ds_read_b64_tr_b16 v[100:101], v206 offset:0x600
	ds_read_b64_tr_b16 v[102:103], v206 offset:0xe00
	v_mfma_f32_32x32x16_bf16 v[32:47], v[68:71], v[104:107], v[32:47]
	ds_read_b64_tr_b16 v[104:105], v206 offset:0x1600
	ds_read_b64_tr_b16 v[106:107], v206 offset:0x1e00
	v_mfma_f32_32x32x16_bf16 v[32:47], v[72:75], v[108:111], v[32:47]
	ds_read_b64_tr_b16 v[108:109], v206 offset:0x2600
	ds_read_b64_tr_b16 v[110:111], v206 offset:0x2e00
	v_mfma_f32_32x32x16_bf16 v[32:47], v[76:79], v[220:223], v[32:47]
	ds_read_b64_tr_b16 v[220:221], v206 offset:0x3600
	ds_read_b64_tr_b16 v[222:223], v206 offset:0x3e00
	s_waitcnt lgkmcnt(0)
	v_mfma_f32_32x32x16_bf16 v[48:63], v[64:67], v[100:103], v[48:63]
	s_waitcnt vmcnt(5)
	ds_write_b128 v211, v[146:149] offset:32768
	s_waitcnt vmcnt(3)
	ds_write_b128 v212, v[150:153] offset:32768
	ds_write_b128 v213, v[154:157] offset:32768
	s_waitcnt vmcnt(2)
	ds_write_b128 v214, v[158:161] offset:32768
	s_waitcnt lgkmcnt(0)
	s_barrier
	v_mfma_f32_32x32x16_bf16 v[48:63], v[68:71], v[104:107], v[48:63]
	v_mfma_f32_32x32x16_bf16 v[48:63], v[72:75], v[108:111], v[48:63]
	v_mfma_f32_32x32x16_bf16 v[48:63], v[76:79], v[220:223], v[48:63]
	ds_read_b128 v[64:67], v207 offset:32768
	ds_read_b128 v[100:103], v208 offset:32768
	s_add_i32 s2, 0, 0x18000
	s_waitcnt lgkmcnt(1)
	v_mfma_f32_32x32x16_bf16 v[64:79], v[64:67], v[142:145], 0
	s_waitcnt lgkmcnt(0)
	v_mfma_f32_32x32x16_bf16 v[64:79], v[100:103], v[138:141], v[64:79]
	ds_read_b128 v[100:103], v209 offset:32768
	s_waitcnt lgkmcnt(0)
	v_mfma_f32_32x32x16_bf16 v[64:79], v[100:103], v[112:115], v[64:79]
	ds_read_b128 v[100:103], v210 offset:32768
	s_waitcnt lgkmcnt(0)
	v_mfma_f32_32x32x16_bf16 v[64:79], v[100:103], v[116:119], v[64:79]
	ds_read_b128 v[100:103], v190 offset:32768
	s_waitcnt lgkmcnt(0)
	v_mfma_f32_32x32x16_bf16 v[64:79], v[100:103], v[120:123], v[64:79]
	ds_read_b128 v[100:103], v191 offset:32768
	s_waitcnt lgkmcnt(0)
	v_mfma_f32_32x32x16_bf16 v[64:79], v[100:103], v[124:127], v[64:79]
	ds_read_b128 v[100:103], v192 offset:32768
	s_waitcnt lgkmcnt(0)
	v_mfma_f32_32x32x16_bf16 v[64:79], v[100:103], v[130:133], v[64:79]
	ds_read_b128 v[100:103], v193 offset:32768
	s_waitcnt lgkmcnt(0)
	v_and_b32_e32 v190, 63, v195
	v_lshlrev_b32_e32 v191, 4, v195
	v_and_b32_e32 v192, 31, v195
	v_bfe_u32 v193, v195, 5, 1
	v_mfma_f32_32x32x16_bf16 v[64:79], v[100:103], v[134:137], v[64:79]
	v_mfma_f32_32x32x16_bf16 v[96:111], v[96:99], v[142:145], 0
	s_nop 10
	v_exp_f32_e32 v72, v80
	v_exp_f32_e32 v80, v81
	v_exp_f32_e32 v73, v82
	v_exp_f32_e32 v81, v83
	v_exp_f32_e32 v74, v84
	v_add_f32_e32 v84, 0, v72
	v_exp_f32_e32 v82, v85
	v_mfma_f32_32x32x16_bf16 v[96:111], v[170:173], v[138:141], v[96:111]
	v_add_f32_e32 v84, v80, v84
	v_exp_f32_e32 v75, v86
	v_add_f32_e32 v84, v73, v84
	v_exp_f32_e32 v83, v87
	v_add_f32_e32 v84, v81, v84
	v_exp_f32_e32 v76, v88
	v_add_f32_e32 v84, v74, v84
	v_mfma_f32_32x32x16_bf16 v[96:111], v[162:165], v[112:115], v[96:111]
	v_exp_f32_e32 v85, v89
	v_add_f32_e32 v84, v82, v84
	v_exp_f32_e32 v77, v90
	v_add_f32_e32 v84, v75, v84
	v_exp_f32_e32 v87, v91
	v_add_f32_e32 v84, v83, v84
	v_exp_f32_e32 v78, v92
	v_mfma_f32_32x32x16_bf16 v[96:111], v[166:169], v[116:119], v[96:111]
	v_add_f32_e32 v84, v76, v84
	v_exp_f32_e32 v89, v93
	v_add_f32_e32 v84, v85, v84
	v_exp_f32_e32 v79, v94
	v_add_f32_e32 v84, v77, v84
	v_exp_f32_e32 v90, v95
	v_add_f32_e32 v84, v87, v84
	v_mfma_f32_32x32x16_bf16 v[96:111], v[174:177], v[120:123], v[96:111]
	v_add_f32_e32 v84, v78, v84
	v_add_f32_e32 v84, v89, v84
	v_add_f32_e32 v84, v79, v84
	v_add_f32_e32 v84, v90, v84
	v_lshl_add_u32 v88, v247, 2, s2
	v_cvt_pk_bf16_f32 v72, v72, v80
	v_cvt_pk_bf16_f32 v73, v73, v81
	v_mfma_f32_32x32x16_bf16 v[96:111], v[178:181], v[124:127], v[96:111]
	v_cvt_pk_bf16_f32 v74, v74, v82
	v_cvt_pk_bf16_f32 v75, v75, v83
	v_cvt_pk_bf16_f32 v76, v76, v85
	v_cvt_pk_bf16_f32 v77, v77, v87
	v_cvt_pk_bf16_f32 v78, v78, v89
	v_cvt_pk_bf16_f32 v79, v79, v90
	s_nop 0
	v_permlane32_swap_b32_e32 v72, v74
	v_mfma_f32_32x32x16_bf16 v[96:111], v[182:185], v[130:133], v[96:111]
	v_permlane32_swap_b32_e32 v73, v75
	v_permlane32_swap_b32_e32 v76, v78
	v_permlane32_swap_b32_e32 v77, v79
	v_mfma_f32_32x32x16_bf16 v[96:111], v[186:189], v[134:137], v[96:111]
	s_nop 11
	v_exp_f32_e32 v91, v96
	v_exp_f32_e32 v92, v97
	v_exp_f32_e32 v93, v98
	v_exp_f32_e32 v94, v99
	v_exp_f32_e32 v95, v100
	v_add_f32_e32 v84, v84, v91
	v_exp_f32_e32 v96, v101
	v_add_f32_e32 v84, v92, v84
	v_exp_f32_e32 v97, v102
	v_add_f32_e32 v84, v93, v84
	v_exp_f32_e32 v98, v103
	v_add_f32_e32 v84, v94, v84
	v_exp_f32_e32 v99, v104
	v_add_f32_e32 v84, v95, v84
	v_exp_f32_e32 v100, v105
	v_add_f32_e32 v84, v96, v84
	v_exp_f32_e32 v101, v106
	v_add_f32_e32 v84, v97, v84
	v_exp_f32_e32 v102, v107
	v_add_f32_e32 v84, v98, v84
	v_exp_f32_e32 v103, v108
	v_add_f32_e32 v84, v99, v84
	v_exp_f32_e32 v104, v109
	v_add_f32_e32 v84, v100, v84
	v_exp_f32_e32 v105, v110
	v_add_f32_e32 v84, v101, v84
	v_exp_f32_e32 v106, v111
	v_add_f32_e32 v84, v102, v84
	v_add_f32_e32 v84, v103, v84
	v_add_f32_e32 v84, v104, v84
	v_add_f32_e32 v84, v105, v84
	v_add_f32_e32 v84, v106, v84
	v_mov_b32_e32 v86, v84
	s_nop 1
	v_permlane32_swap_b32_e32 v84, v86
	v_cvt_pk_bf16_f32 v80, v91, v92
	v_cvt_pk_bf16_f32 v81, v93, v94
	v_cvt_pk_bf16_f32 v82, v95, v96
	v_cvt_pk_bf16_f32 v83, v97, v98
	v_cvt_pk_bf16_f32 v90, v99, v100
	v_cvt_pk_bf16_f32 v91, v101, v102
	v_cvt_pk_bf16_f32 v92, v103, v104
	v_cvt_pk_bf16_f32 v93, v105, v106
	s_nop 0
	v_permlane32_swap_b32_e32 v80, v82
	v_permlane32_swap_b32_e32 v81, v83
	v_permlane32_swap_b32_e32 v90, v92
	v_permlane32_swap_b32_e32 v91, v93
	ds_read_b64_tr_b16 v[94:95], v206 offset:0x4000
	ds_read_b64_tr_b16 v[96:97], v206 offset:0x4800
	ds_read_b64_tr_b16 v[98:99], v206 offset:0x5000
	ds_read_b64_tr_b16 v[100:101], v206 offset:0x5800
	ds_read_b64_tr_b16 v[102:103], v206 offset:0x6000
	ds_read_b64_tr_b16 v[104:105], v206 offset:0x6800
	ds_read_b64_tr_b16 v[106:107], v206 offset:0x7000
	ds_read_b64_tr_b16 v[108:109], v206 offset:0x7800
	s_waitcnt lgkmcnt(0)
; #define SBAR() __builtin_amdgcn_sched_barrier(0)
; __device__ __forceinline__ int crow(int r, int hi) { return (r & 3) + 8 * (r >> 2) + 4 * hi; }
; #define NOP_() do { } while (0)
; template <int D0, int BOFF> __device__ __forceinline__ void pv_one_i(f32x16& od, int vb, bf16x8 pa0, bf16x8 pa1, bf16x8 pa2, bf16x8 pa3) {
;   const s16x4 l0 = tr_read<BOFF + v_rd_off(D0, 0, 0)>(vb), h0 = tr_read<BOFF + v_rd_off(D0, 0, 1)>(vb), l1 = tr_read<BOFF + v_rd_off(D0, 1, 0)>(vb), h1 = tr_read<BOFF + v_rd_off(D0, 1, 1)>(vb);
;   const s16x4 l2 = tr_read<BOFF + v_rd_off(D0, 2, 0)>(vb), h2 = tr_read<BOFF + v_rd_off(D0, 2, 1)>(vb), l3 = tr_read<BOFF + v_rd_off(D0, 3, 0)>(vb), h3 = tr_read<BOFF + v_rd_off(D0, 3, 1)>(vb);
;   asm volatile("s_waitcnt lgkmcnt(0)" ::: "memory"); SBAR();
;     ...
;   od = __builtin_amdgcn_mfma_f32_32x32x16_bf16(pa0, PK(l0, h0), od, 0, 0, 0);
;   od = __builtin_amdgcn_mfma_f32_32x32x16_bf16(pa1, PK(l1, h1), od, 0, 0, 0);
;   od = __builtin_amdgcn_mfma_f32_32x32x16_bf16(pa2, PK(l2, h2), od, 0, 0, 0);
;   od = __builtin_amdgcn_mfma_f32_32x32x16_bf16(pa3, PK(l3, h3), od, 0, 0, 0);
;     ...
; }
; template <int BOFF> __device__ __forceinline__ void pv_i(f32x16* o, int vb, bf16x8 pa0, bf16x8 pa1, bf16x8 pa2, bf16x8 pa3) {
;   pv_one_i<0, BOFF>(o[0], vb, pa0, pa1, pa2, pa3); pv_one_i<1, BOFF>(o[1], vb, pa0, pa1, pa2, pa3); pv_one_i<2, BOFF>(o[2], vb, pa0, pa1, pa2, pa3); pv_one_i<3, BOFF>(o[3], vb, pa0, pa1, pa2, pa3);
; template <bool PARTIAL, bool FIXED> ...
;     ...
;   HALF_A(2, 1, do { if (mask_last) { asm volatile("; masked tail tile" ::: "memory"); const float NEG = -INFINITY; \
;       _Pragma("unroll") for (int r = 8; r < 16; ++r) pA0[r] = NEG; _Pragma("unroll") for (int r = 0; r < 16; ++r) pA1[r] = NEG; } } while (0), NOP_(), NOP_());
;     ...
;   SBAR(); finishSM(pA0, pA1, alA, l_reg, pa0, pa1, pa2, pa3); SBAR();
;   pv_i<2 * 16384>(o, vbi, pa0, pa1, pa2, pa3);
;     ...
;   if (PARTIAL) {
;     if (wid < 2) { float* po = PO + (wid * QBLK) * 128;
; #pragma unroll
;       for (int r = 0; r < 16; ++r) { const int orow = crow(r, hi);
; #pragma unroll
;         for (int d0 = 0; d0 < 4; ++d0) po[orow * 128 + d0 * 32 + r32] = o[d0][r]; }
;       if (hi == 0) { PO[8192 + (wid * QBLK + r32) * 2] = m_reg; PO[8192 + (wid * QBLK + r32) * 2 + 1] = l_reg; } }
;     __syncthreads();
;     return;
;   }
;   if (hi == 0) li_l[r32] = l_reg; asm volatile("s_waitcnt lgkmcnt(0)" ::: "memory");
	s_nop 0
	v_mfma_f32_32x32x16_bf16 v[0:15], v[72:75], v[94:97], v[0:15]
	ds_read_b64_tr_b16 v[94:95], v206 offset:0x4200
	ds_read_b64_tr_b16 v[96:97], v206 offset:0x4a00
	v_mfma_f32_32x32x16_bf16 v[0:15], v[76:79], v[98:101], v[0:15]
	ds_read_b64_tr_b16 v[98:99], v206 offset:0x5200
	ds_read_b64_tr_b16 v[100:101], v206 offset:0x5a00
	v_mfma_f32_32x32x16_bf16 v[0:15], v[80:83], v[102:105], v[0:15]
	ds_read_b64_tr_b16 v[102:103], v206 offset:0x6200
	ds_read_b64_tr_b16 v[104:105], v206 offset:0x6a00
	v_mfma_f32_32x32x16_bf16 v[0:15], v[90:93], v[106:109], v[0:15]
	ds_read_b64_tr_b16 v[106:107], v206 offset:0x7200
	ds_read_b64_tr_b16 v[108:109], v206 offset:0x7a00
	s_waitcnt lgkmcnt(0)
	v_mfma_f32_32x32x16_bf16 v[16:31], v[72:75], v[94:97], v[16:31]
	ds_read_b64_tr_b16 v[94:95], v206 offset:0x4400
	ds_read_b64_tr_b16 v[96:97], v206 offset:0x4c00
	v_mfma_f32_32x32x16_bf16 v[16:31], v[76:79], v[98:101], v[16:31]
	ds_read_b64_tr_b16 v[98:99], v206 offset:0x5400
	ds_read_b64_tr_b16 v[100:101], v206 offset:0x5c00
	v_mfma_f32_32x32x16_bf16 v[16:31], v[80:83], v[102:105], v[16:31]
	ds_read_b64_tr_b16 v[102:103], v206 offset:0x6400
	ds_read_b64_tr_b16 v[104:105], v206 offset:0x6c00
	v_mfma_f32_32x32x16_bf16 v[16:31], v[90:93], v[106:109], v[16:31]
	ds_read_b64_tr_b16 v[106:107], v206 offset:0x7400
	ds_read_b64_tr_b16 v[108:109], v206 offset:0x7c00
	s_waitcnt lgkmcnt(0)
	v_mfma_f32_32x32x16_bf16 v[32:47], v[72:75], v[94:97], v[32:47]
	ds_read_b64_tr_b16 v[94:95], v206 offset:0x4600
	ds_read_b64_tr_b16 v[96:97], v206 offset:0x4e00
	v_mfma_f32_32x32x16_bf16 v[32:47], v[76:79], v[98:101], v[32:47]
	ds_read_b64_tr_b16 v[98:99], v206 offset:0x5600
	ds_read_b64_tr_b16 v[100:101], v206 offset:0x5e00
	v_mfma_f32_32x32x16_bf16 v[32:47], v[80:83], v[102:105], v[32:47]
	ds_read_b64_tr_b16 v[102:103], v206 offset:0x6600
	ds_read_b64_tr_b16 v[104:105], v206 offset:0x6e00
	v_mfma_f32_32x32x16_bf16 v[32:47], v[90:93], v[106:109], v[32:47]
	ds_read_b64_tr_b16 v[106:107], v206 offset:0x7600
	ds_read_b64_tr_b16 v[108:109], v206 offset:0x7e00
	s_waitcnt lgkmcnt(0)
	v_mfma_f32_32x32x16_bf16 v[48:63], v[72:75], v[94:97], v[48:63]
	v_exp_f32_e32 v64, v64
	v_exp_f32_e32 v65, v65
	v_exp_f32_e32 v66, v66
	v_exp_f32_e32 v67, v67
	v_exp_f32_e32 v68, v68
	v_exp_f32_e32 v69, v69
	v_exp_f32_e32 v70, v70
	v_mfma_f32_32x32x16_bf16 v[48:63], v[76:79], v[98:101], v[48:63]
	v_exp_f32_e32 v71, v71
	v_mfma_f32_32x32x16_bf16 v[48:63], v[80:83], v[102:105], v[48:63]
	v_mfma_f32_32x32x16_bf16 v[48:63], v[90:93], v[106:109], v[48:63]
	v_add_f32_e32 v72, 0, v64
	v_add_f32_e32 v72, v65, v72
	v_add_f32_e32 v72, v66, v72
	v_add_f32_e32 v72, v67, v72
	v_add_f32_e32 v72, v68, v72
	v_add_f32_e32 v72, v69, v72
	v_add_f32_e32 v72, v70, v72
	v_add_f32_e32 v72, v71, v72
	v_add_f32_e32 v85, 0, v72
	v_mov_b32_e32 v87, v85
	s_nop 1
	v_permlane32_swap_b32_e32 v85, v87
	v_cvt_pk_bf16_f32 v64, v64, v65
	v_cvt_pk_bf16_f32 v65, v66, v67
	v_cvt_pk_bf16_f32 v66, v68, v69
	v_cvt_pk_bf16_f32 v67, v70, v71
	v_cvt_pk_bf16_f32 v68, v129, v129
	v_cvt_pk_bf16_f32 v69, v129, v129
	v_cvt_pk_bf16_f32 v70, v129, v129
	v_cvt_pk_bf16_f32 v71, v129, v129
	v_cvt_pk_bf16_f32 v72, v129, v129
	v_cvt_pk_bf16_f32 v73, v129, v129
	v_cvt_pk_bf16_f32 v74, v129, v129
	v_cvt_pk_bf16_f32 v75, v129, v129
	v_cvt_pk_bf16_f32 v76, v129, v129
	v_cvt_pk_bf16_f32 v77, v129, v129
	v_cvt_pk_bf16_f32 v78, v129, v129
	v_cvt_pk_bf16_f32 v79, v129, v129
	s_nop 0
	v_permlane32_swap_b32_e32 v64, v66
	v_permlane32_swap_b32_e32 v65, v67
	v_permlane32_swap_b32_e32 v68, v70
	v_permlane32_swap_b32_e32 v69, v71
	v_permlane32_swap_b32_e32 v72, v74
	v_permlane32_swap_b32_e32 v73, v75
	v_permlane32_swap_b32_e32 v76, v78
	v_permlane32_swap_b32_e32 v77, v79
	ds_read_b64_tr_b16 v[80:81], v206 offset:0x8000
	ds_read_b64_tr_b16 v[82:83], v206 offset:0x8800
	ds_read_b64_tr_b16 v[90:91], v206 offset:0x9000
	ds_read_b64_tr_b16 v[92:93], v206 offset:0x9800
	ds_read_b64_tr_b16 v[94:95], v206 offset:0xa000
	ds_read_b64_tr_b16 v[96:97], v206 offset:0xa800
	ds_read_b64_tr_b16 v[98:99], v206 offset:0xb000
	ds_read_b64_tr_b16 v[100:101], v206 offset:0xb800
	s_waitcnt lgkmcnt(0)
	s_nop 0
	v_mfma_f32_32x32x16_bf16 v[0:15], v[64:67], v[80:83], v[0:15]
	ds_read_b64_tr_b16 v[80:81], v206 offset:0x8200
	ds_read_b64_tr_b16 v[82:83], v206 offset:0x8a00
	v_mfma_f32_32x32x16_bf16 v[0:15], v[68:71], v[90:93], v[0:15]
	ds_read_b64_tr_b16 v[90:91], v206 offset:0x9200
	ds_read_b64_tr_b16 v[92:93], v206 offset:0x9a00
	v_mfma_f32_32x32x16_bf16 v[0:15], v[72:75], v[94:97], v[0:15]
	ds_read_b64_tr_b16 v[94:95], v206 offset:0xa200
	ds_read_b64_tr_b16 v[96:97], v206 offset:0xaa00
	v_mfma_f32_32x32x16_bf16 v[0:15], v[76:79], v[98:101], v[0:15]
	ds_read_b64_tr_b16 v[98:99], v206 offset:0xb200
	ds_read_b64_tr_b16 v[100:101], v206 offset:0xba00
	s_waitcnt lgkmcnt(0)
	v_mfma_f32_32x32x16_bf16 v[16:31], v[64:67], v[80:83], v[16:31]
	ds_read_b64_tr_b16 v[80:81], v206 offset:0x8400
	ds_read_b64_tr_b16 v[82:83], v206 offset:0x8c00
	v_mfma_f32_32x32x16_bf16 v[16:31], v[68:71], v[90:93], v[16:31]
	ds_read_b64_tr_b16 v[90:91], v206 offset:0x9400
	ds_read_b64_tr_b16 v[92:93], v206 offset:0x9c00
	v_mfma_f32_32x32x16_bf16 v[16:31], v[72:75], v[94:97], v[16:31]
	ds_read_b64_tr_b16 v[94:95], v206 offset:0xa400
	ds_read_b64_tr_b16 v[96:97], v206 offset:0xac00
	v_mfma_f32_32x32x16_bf16 v[16:31], v[76:79], v[98:101], v[16:31]
	ds_read_b64_tr_b16 v[98:99], v206 offset:0xb400
	ds_read_b64_tr_b16 v[100:101], v206 offset:0xbc00
	s_waitcnt lgkmcnt(0)
	v_mfma_f32_32x32x16_bf16 v[32:47], v[64:67], v[80:83], v[32:47]
	ds_read_b64_tr_b16 v[80:81], v206 offset:0x8600
	ds_read_b64_tr_b16 v[82:83], v206 offset:0x8e00
	v_mfma_f32_32x32x16_bf16 v[32:47], v[68:71], v[90:93], v[32:47]
	ds_read_b64_tr_b16 v[90:91], v206 offset:0x9600
	ds_read_b64_tr_b16 v[92:93], v206 offset:0x9e00
	v_mfma_f32_32x32x16_bf16 v[32:47], v[72:75], v[94:97], v[32:47]
	ds_read_b64_tr_b16 v[94:95], v206 offset:0xa600
	ds_read_b64_tr_b16 v[96:97], v206 offset:0xae00
	v_mfma_f32_32x32x16_bf16 v[32:47], v[76:79], v[98:101], v[32:47]
	ds_read_b64_tr_b16 v[98:99], v206 offset:0xb600
	ds_read_b64_tr_b16 v[100:101], v206 offset:0xbe00
	s_waitcnt lgkmcnt(0)
	v_mfma_f32_32x32x16_bf16 v[48:63], v[64:67], v[80:83], v[48:63]
	v_cmp_gt_u32_e32 vcc, 32, v190
	v_mfma_f32_32x32x16_bf16 v[48:63], v[68:71], v[90:93], v[48:63]
	v_mfma_f32_32x32x16_bf16 v[48:63], v[72:75], v[94:97], v[48:63]
	v_mfma_f32_32x32x16_bf16 v[48:63], v[76:79], v[98:101], v[48:63]
	s_and_saveexec_b64 s[28:29], vcc
	s_cbranch_execz .LBB0_309
	v_add_f32_e32 v64, v128, v218
	v_add_f32_e32 v66, v215, v64
	v_pk_add_f32 v[64:65], v[84:85], v[86:87]
	v_lshl_add_u32 v67, v192, 2, v88
	v_add_f32_e32 v64, v66, v64
	v_add_f32_e32 v64, v64, v65
	ds_write_b32 v67, v64
	s_branch .LBB0_309
